# attention: removed always-satisfied lgkmcnt waits in front of QK MFMAs (256 sites)
# speedup vs baseline: 1.0129x; 1.0020x over previous
.LBB0_878:
	v_add_u32_e32 v183, s96, v209
	ds_read_b64_tr_b16 v[178:179], v183 offset:24576
	ds_read_b64_tr_b16 v[180:181], v183 offset:25088
	v_mfma_f32_32x32x16_bf16 v[98:113], v[82:85], v[142:145], v[34:49]
	v_add_f32_e32 v86, v66, v67
	v_add_f32_e32 v86, v68, v86
	v_add_f32_e32 v86, v69, v86
	v_add_f32_e32 v86, v70, v86
	v_add_f32_e32 v86, v71, v86
	v_cvt_pk_bf16_f32 v158, v66, v67
	v_cvt_pk_bf16_f32 v159, v68, v69
	ds_read_b64_tr_b16 v[174:175], v183 offset:28672
	ds_read_b64_tr_b16 v[176:177], v183 offset:29184
	v_add_f32_e32 v66, v72, v86
	v_mfma_f32_32x32x16_bf16 v[82:97], v[170:173], v[142:145], v[34:49]
	v_add_f32_e32 v66, v73, v66
	v_add_f32_e32 v66, v74, v66
	v_add_f32_e32 v66, v75, v66
	v_cvt_pk_bf16_f32 v160, v70, v71
	v_cvt_pk_bf16_f32 v161, v72, v73
	ds_read_b64_tr_b16 v[170:171], v183 offset:25600
	ds_read_b64_tr_b16 v[172:173], v183 offset:26112
	v_mfma_f32_32x32x16_bf16 v[98:113], v[166:169], v[138:141], v[98:113]
	v_add_f32_e32 v66, v76, v66
	v_add_f32_e32 v66, v77, v66
	v_add_f32_e32 v66, v78, v66
	v_add_f32_e32 v66, v79, v66
	v_cvt_pk_bf16_f32 v154, v74, v75
	v_cvt_pk_bf16_f32 v155, v76, v77
	ds_read_b64_tr_b16 v[74:75], v183 offset:29696
	ds_read_b64_tr_b16 v[76:77], v183 offset:30208
	v_mfma_f32_32x32x16_bf16 v[82:97], v[162:165], v[138:141], v[82:97]
	v_add_f32_e32 v66, v80, v66
	v_add_f32_e32 v66, v81, v66
	v_add_f32_e32 v66, v50, v66
	v_add_f32_e32 v66, v51, v66
	v_cvt_pk_bf16_f32 v156, v78, v79
	v_cvt_pk_bf16_f32 v157, v80, v81
	ds_read_b64_tr_b16 v[70:71], v183 offset:26624
	ds_read_b64_tr_b16 v[72:73], v183 offset:27136
	v_mfma_f32_32x32x16_bf16 v[98:113], v[126:129], v[134:137], v[98:113]
	v_add_f32_e32 v66, v52, v66
	v_add_f32_e32 v66, v53, v66
	v_add_f32_e32 v66, v54, v66
	v_add_f32_e32 v78, v55, v66
	v_cvt_pk_bf16_f32 v150, v50, v51
	v_cvt_pk_bf16_f32 v151, v52, v53
	ds_read_b64_tr_b16 v[66:67], v183 offset:30720
	ds_read_b64_tr_b16 v[68:69], v183 offset:31232
	v_mfma_f32_32x32x16_bf16 v[82:97], v[122:125], v[134:137], v[82:97]
	v_add_f32_e32 v50, v56, v78
	v_add_f32_e32 v50, v57, v50
	v_add_f32_e32 v50, v58, v50
	v_add_f32_e32 v50, v59, v50
	v_cvt_pk_bf16_f32 v152, v54, v55
	v_cvt_pk_bf16_f32 v153, v56, v57
	ds_read_b64_tr_b16 v[54:55], v183 offset:27648
	ds_read_b64_tr_b16 v[56:57], v183 offset:28160
	v_mfma_f32_32x32x16_bf16 v[98:113], v[118:121], v[130:133], v[98:113]
	v_add_f32_e32 v50, v60, v50
	v_add_f32_e32 v50, v61, v50
	v_add_f32_e32 v50, v62, v50
	v_add_f32_e32 v78, v63, v50
	v_cvt_pk_bf16_f32 v146, v58, v59
	v_cvt_pk_bf16_f32 v147, v60, v61
	ds_read_b64_tr_b16 v[50:51], v183 offset:31744
	ds_read_b64_tr_b16 v[52:53], v183 offset:32256
	v_mfma_f32_32x32x16_bf16 v[82:97], v[114:117], v[130:133], v[82:97]
	v_add_f32_e32 v58, v64, v78
	v_add_f32_e32 v58, v65, v58
	v_add_f32_e32 v60, 0, v58
	v_cvt_pk_bf16_f32 v148, v62, v63
	v_cvt_pk_bf16_f32 v149, v64, v65
	v_lshl_add_u64 v[58:59], v[196:197], 0, s[30:31]
	s_add_i32 s15, s64, s94
	s_mov_b32 s19, m0
	s_mov_b32 m0, s15
	s_nop 0
	global_load_lds_dwordx4 v[58:59], off
	s_mov_b32 m0, s19
	v_lshl_add_u64 v[58:59], v[188:189], 0, s[26:27]
	s_add_i32 s15, s18, s93
	s_mov_b32 s19, m0
	s_mov_b32 m0, s15
	s_nop 0
	global_load_lds_dwordx4 v[58:59], off
	s_mov_b32 m0, s19
	v_max_f32_e32 v58, v99, v99
	v_max_f32_e32 v59, v98, v98
	v_max_f32_e32 v58, v59, v58
	v_max3_f32 v59, v100, v101, v83
	v_max3_f32 v58, v58, v82, v84
	v_max3_f32 v58, v58, v85, v102
	v_max3_f32 v59, v59, v104, v105
	v_max3_f32 v58, v58, v103, v86
	v_max3_f32 v59, v59, v88, v89
	v_max3_f32 v58, v58, v87, v106
	v_max3_f32 v59, v59, v108, v109
	v_max3_f32 v58, v58, v107, v90
	v_max3_f32 v59, v59, v92, v93
	v_max3_f32 v58, v58, v91, v110
	v_max3_f32 v59, v59, v112, v113
	v_max3_f32 v58, v58, v111, v94
	v_max3_f32 v59, v59, v96, v97
	v_max3_f32 v58, v58, v95, v59
	v_mov_b32_e32 v59, v58
	s_nop 1
	v_permlane32_swap_b32_e32 v58, v59
	v_max_f32_e32 v59, v59, v59
	v_max_f32_e32 v58, v58, v58
	v_max_f32_e32 v58, v58, v59
	v_cmp_lt_f32_e32 vcc, s83, v58
	s_cmp_lg_u64 vcc, 0
	v_add_f32_e32 v213, v182, v60
	s_cselect_b64 s[60:61], -1, 0
	s_cbranch_vccnz .LBB0_886

.LBB0_881:
	s_add_i32 s15, s18, 0x2000
	s_cmpk_lg_i32 s18, 0x4000
	s_cselect_b32 s65, s15, 0
	v_add_u32_e32 v214, s64, v209
	ds_read_b64_tr_b16 v[126:127], v214 offset:24576
	ds_read_b64_tr_b16 v[128:129], v214 offset:25088
	v_mfma_f32_32x32x16_bf16 v[66:81], v[58:61], v[142:145], v[34:49]
	v_add_f32_e32 v50, v98, v99
	v_add_f32_e32 v50, v100, v50
	v_add_f32_e32 v50, v101, v50
	v_add_f32_e32 v50, v102, v50
	v_add_f32_e32 v50, v103, v50
	v_cvt_pk_bf16_f32 v158, v98, v99
	v_cvt_pk_bf16_f32 v159, v100, v101
	ds_read_b64_tr_b16 v[122:123], v214 offset:28672
	ds_read_b64_tr_b16 v[124:125], v214 offset:29184
	v_add_f32_e32 v50, v104, v50
	v_add_f32_e32 v50, v105, v50
	v_add_f32_e32 v50, v106, v50
	v_add_f32_e32 v98, v107, v50
	v_mfma_f32_32x32x16_bf16 v[50:65], v[114:117], v[142:145], v[34:49]
	v_cvt_pk_bf16_f32 v160, v102, v103
	v_cvt_pk_bf16_f32 v161, v104, v105
	ds_read_b64_tr_b16 v[118:119], v214 offset:25600
	ds_read_b64_tr_b16 v[120:121], v214 offset:26112
	v_mfma_f32_32x32x16_bf16 v[66:81], v[182:185], v[138:141], v[66:81]
	v_add_f32_e32 v98, v108, v98
	v_add_f32_e32 v98, v109, v98
	v_add_f32_e32 v98, v110, v98
	v_add_f32_e32 v98, v111, v98
	v_cvt_pk_bf16_f32 v154, v106, v107
	v_cvt_pk_bf16_f32 v155, v108, v109
	ds_read_b64_tr_b16 v[114:115], v214 offset:29696
	ds_read_b64_tr_b16 v[116:117], v214 offset:30208
	v_mfma_f32_32x32x16_bf16 v[50:65], v[174:177], v[138:141], v[50:65]
	v_add_f32_e32 v98, v112, v98
	v_add_f32_e32 v98, v113, v98
	v_add_f32_e32 v98, v82, v98
	v_add_f32_e32 v98, v83, v98
	v_cvt_pk_bf16_f32 v156, v110, v111
	v_cvt_pk_bf16_f32 v157, v112, v113
	ds_read_b64_tr_b16 v[106:107], v214 offset:26624
	ds_read_b64_tr_b16 v[108:109], v214 offset:27136
	v_mfma_f32_32x32x16_bf16 v[66:81], v[178:181], v[134:137], v[66:81]
	v_add_f32_e32 v98, v84, v98
	v_add_f32_e32 v98, v85, v98
	v_add_f32_e32 v98, v86, v98
	v_add_f32_e32 v98, v87, v98
	v_cvt_pk_bf16_f32 v150, v82, v83
	v_cvt_pk_bf16_f32 v151, v84, v85
	ds_read_b64_tr_b16 v[102:103], v214 offset:30720
	ds_read_b64_tr_b16 v[104:105], v214 offset:31232
	v_mfma_f32_32x32x16_bf16 v[50:65], v[166:169], v[134:137], v[50:65]
	v_add_f32_e32 v82, v88, v98
	v_add_f32_e32 v82, v89, v82
	v_add_f32_e32 v82, v90, v82
	v_add_f32_e32 v82, v91, v82
	v_cvt_pk_bf16_f32 v152, v86, v87
	v_cvt_pk_bf16_f32 v153, v88, v89
	ds_read_b64_tr_b16 v[98:99], v214 offset:27648
	ds_read_b64_tr_b16 v[100:101], v214 offset:28160
	v_mfma_f32_32x32x16_bf16 v[66:81], v[170:173], v[130:133], v[66:81]
	v_add_f32_e32 v82, v92, v82
	v_add_f32_e32 v82, v93, v82
	v_add_f32_e32 v82, v94, v82
	v_add_f32_e32 v82, v95, v82
	v_cvt_pk_bf16_f32 v146, v90, v91
	v_cvt_pk_bf16_f32 v147, v92, v93
	ds_read_b64_tr_b16 v[86:87], v214 offset:31744
	ds_read_b64_tr_b16 v[88:89], v214 offset:32256
	v_mfma_f32_32x32x16_bf16 v[50:65], v[162:165], v[130:133], v[50:65]
	v_add_f32_e32 v82, v96, v82
	v_add_f32_e32 v82, v97, v82
	v_add_f32_e32 v84, 0, v82
	v_cvt_pk_bf16_f32 v148, v94, v95
	v_cvt_pk_bf16_f32 v149, v96, v97
	v_lshl_add_u64 v[82:83], v[196:197], 0, s[34:35]
	s_add_i32 s15, s18, s94
	s_mov_b32 s19, m0
	s_mov_b32 m0, s15
	s_nop 0
	global_load_lds_dwordx4 v[82:83], off
	s_mov_b32 m0, s19
	v_max_f32_e32 v82, v67, v67
	v_max_f32_e32 v83, v66, v66
	v_max_f32_e32 v82, v83, v82
	s_nop 1
	v_max3_f32 v83, v68, v69, v51
	v_max3_f32 v82, v82, v50, v52
	v_max3_f32 v82, v82, v53, v70
	v_max3_f32 v83, v83, v72, v73
	v_max3_f32 v82, v82, v71, v54
	v_max3_f32 v83, v83, v56, v57
	v_max3_f32 v82, v82, v55, v74
	v_max3_f32 v83, v83, v76, v77
	v_max3_f32 v82, v82, v75, v58
	v_max3_f32 v83, v83, v60, v61
	v_max3_f32 v82, v82, v59, v78
	v_max3_f32 v83, v83, v80, v81
	v_max3_f32 v82, v82, v79, v62
	v_max3_f32 v83, v83, v64, v65
	v_max3_f32 v82, v82, v63, v83
	v_mov_b32_e32 v83, v82
	s_nop 1
	v_permlane32_swap_b32_e32 v82, v83
	v_max_f32_e32 v83, v83, v83
	v_max_f32_e32 v82, v82, v82
	v_max_f32_e32 v82, v82, v83
	v_lshl_add_u64 v[188:189], v[188:189], 0, s[28:29]
	s_add_i32 s15, s65, s93
	s_mov_b32 s19, m0
	s_mov_b32 m0, s15
	s_nop 0
	global_load_lds_dwordx4 v[188:189], off
	s_mov_b32 m0, s19
	v_cmp_lt_f32_e32 vcc, s83, v82
	s_cmp_lg_u64 vcc, 0
	v_add_f32_e32 v182, v213, v84
	s_cselect_b64 s[60:61], -1, 0
	s_cbranch_vccnz .LBB0_889

.LBB0_895:
	ds_read_b64_tr_b16 v[166:167], v209 offset:40960
	ds_read_b64_tr_b16 v[168:169], v209 offset:41472
	v_mfma_f32_32x32x16_bf16 v[114:129], v[58:61], v[142:145], v[34:49]
	v_add_f32_e32 v50, v98, v99
	v_add_f32_e32 v50, v100, v50
	v_add_f32_e32 v50, v101, v50
	v_add_f32_e32 v50, v102, v50
	v_add_f32_e32 v50, v103, v50
	v_cvt_pk_bf16_f32 v158, v98, v99
	v_cvt_pk_bf16_f32 v159, v100, v101
	ds_read_b64_tr_b16 v[162:163], v209 offset:45056
	ds_read_b64_tr_b16 v[164:165], v209 offset:45568
	v_add_f32_e32 v50, v104, v50
	v_add_f32_e32 v50, v105, v50
	v_add_f32_e32 v50, v106, v50
	v_add_f32_e32 v66, v107, v50
	v_mfma_f32_32x32x16_bf16 v[50:65], v[182:185], v[142:145], v[34:49]
	v_cvt_pk_bf16_f32 v160, v102, v103
	v_cvt_pk_bf16_f32 v161, v104, v105
	ds_read_b64_tr_b16 v[102:103], v209 offset:41984
	ds_read_b64_tr_b16 v[104:105], v209 offset:42496
	v_mfma_f32_32x32x16_bf16 v[114:129], v[186:189], v[138:141], v[114:129]
	v_add_f32_e32 v66, v108, v66
	v_add_f32_e32 v66, v109, v66
	v_add_f32_e32 v66, v110, v66
	v_add_f32_e32 v66, v111, v66
	v_cvt_pk_bf16_f32 v154, v106, v107
	v_cvt_pk_bf16_f32 v155, v108, v109
	ds_read_b64_tr_b16 v[98:99], v209 offset:46080
	ds_read_b64_tr_b16 v[100:101], v209 offset:46592
	v_mfma_f32_32x32x16_bf16 v[50:65], v[78:81], v[138:141], v[50:65]
	v_add_f32_e32 v66, v112, v66
	v_add_f32_e32 v66, v113, v66
	v_add_f32_e32 v66, v82, v66
	v_add_f32_e32 v66, v83, v66
	v_cvt_pk_bf16_f32 v156, v110, v111
	v_cvt_pk_bf16_f32 v157, v112, v113
	ds_read_b64_tr_b16 v[78:79], v209 offset:43008
	ds_read_b64_tr_b16 v[80:81], v209 offset:43520
	v_mfma_f32_32x32x16_bf16 v[114:129], v[74:77], v[134:137], v[114:129]
	v_add_f32_e32 v66, v84, v66
	v_add_f32_e32 v66, v85, v66
	v_add_f32_e32 v66, v86, v66
	v_add_f32_e32 v66, v87, v66
	v_cvt_pk_bf16_f32 v150, v82, v83
	v_cvt_pk_bf16_f32 v151, v84, v85
	ds_read_b64_tr_b16 v[74:75], v209 offset:47104
	ds_read_b64_tr_b16 v[76:77], v209 offset:47616
	v_mfma_f32_32x32x16_bf16 v[50:65], v[174:177], v[134:137], v[50:65]
	v_add_f32_e32 v66, v88, v66
	v_add_f32_e32 v66, v89, v66
	v_add_f32_e32 v66, v90, v66
	v_add_f32_e32 v66, v91, v66
	v_cvt_pk_bf16_f32 v152, v86, v87
	v_cvt_pk_bf16_f32 v153, v88, v89
	ds_read_b64_tr_b16 v[70:71], v209 offset:44032
	ds_read_b64_tr_b16 v[72:73], v209 offset:44544
	v_mfma_f32_32x32x16_bf16 v[114:129], v[178:181], v[130:133], v[114:129]
	v_add_f32_e32 v66, v92, v66
	v_add_f32_e32 v66, v93, v66
	v_add_f32_e32 v66, v94, v66
	v_add_f32_e32 v82, v95, v66
	v_cvt_pk_bf16_f32 v146, v90, v91
	v_cvt_pk_bf16_f32 v147, v92, v93
	ds_read_b64_tr_b16 v[66:67], v209 offset:48128
	ds_read_b64_tr_b16 v[68:69], v209 offset:48640
	v_mfma_f32_32x32x16_bf16 v[50:65], v[170:173], v[130:133], v[50:65]
	v_add_f32_e32 v82, v96, v82
	v_add_f32_e32 v82, v97, v82
	v_add_f32_e32 v82, 0, v82
	v_cvt_pk_bf16_f32 v148, v94, v95
	v_cvt_pk_bf16_f32 v149, v96, v97
	s_cmp_lg_u32 0, -1
	s_cselect_b32 s15, 0, 0
	v_add_f32_e32 v182, v197, v82
	v_lshl_add_u64 v[82:83], v[194:195], 0, s[40:41]
	s_add_i32 s15, s15, s69
	s_add_i32 s15, s15, 0x8000
	s_mov_b32 s18, m0
	s_mov_b32 m0, s15
	s_nop 0
	global_load_lds_dwordx4 v[82:83], off
	s_mov_b32 m0, s18
	v_max_f32_e32 v82, v115, v115
	v_max_f32_e32 v83, v114, v114
	v_max_f32_e32 v82, v83, v82
	v_max3_f32 v83, v116, v117, v51
	v_max3_f32 v82, v82, v50, v52
	v_max3_f32 v82, v82, v53, v118
	v_max3_f32 v83, v83, v120, v121
	v_max3_f32 v82, v82, v119, v54
	v_max3_f32 v83, v83, v56, v57
	v_max3_f32 v82, v82, v55, v122
	v_max3_f32 v83, v83, v124, v125
	v_max3_f32 v82, v82, v123, v58
	v_max3_f32 v83, v83, v60, v61
	v_max3_f32 v82, v82, v59, v126
	v_max3_f32 v83, v83, v128, v129
	v_max3_f32 v82, v82, v127, v62
	v_max3_f32 v83, v83, v64, v65
	v_max3_f32 v82, v82, v63, v83
	v_mov_b32_e32 v83, v82
	s_nop 1
	v_permlane32_swap_b32_e32 v82, v83
	v_max_f32_e32 v83, v83, v83
	v_max_f32_e32 v82, v82, v82
	v_max_f32_e32 v82, v82, v83
	v_cmp_lt_f32_e32 vcc, s83, v82
	s_cmp_lg_u64 vcc, 0
	s_cselect_b64 s[60:61], -1, 0
	s_cbranch_vccnz .LBB0_1002

.LBB0_898:
	ds_read_b64_tr_b16 v[162:163], v209 offset:24576
	ds_read_b64_tr_b16 v[164:165], v209 offset:25088
	v_mfma_f32_32x32x16_bf16 v[82:97], v[110:113], v[142:145], v[34:49]
	v_add_f32_e32 v66, v114, v115
	v_add_f32_e32 v66, v116, v66
	v_add_f32_e32 v66, v117, v66
	v_add_f32_e32 v66, v118, v66
	v_add_f32_e32 v66, v119, v66
	v_cvt_pk_bf16_f32 v158, v114, v115
	v_cvt_pk_bf16_f32 v159, v116, v117
	ds_read_b64_tr_b16 v[114:115], v209 offset:28672
	ds_read_b64_tr_b16 v[116:117], v209 offset:29184
	v_add_f32_e32 v66, v120, v66
	v_add_f32_e32 v66, v121, v66
	v_add_f32_e32 v66, v122, v66
	v_add_f32_e32 v146, v123, v66
	v_mfma_f32_32x32x16_bf16 v[66:81], v[106:109], v[142:145], v[34:49]
	v_cvt_pk_bf16_f32 v160, v118, v119
	v_cvt_pk_bf16_f32 v161, v120, v121
	ds_read_b64_tr_b16 v[110:111], v209 offset:25600
	ds_read_b64_tr_b16 v[112:113], v209 offset:26112
	v_mfma_f32_32x32x16_bf16 v[82:97], v[178:181], v[138:141], v[82:97]
	v_add_f32_e32 v106, v124, v146
	v_add_f32_e32 v106, v125, v106
	v_add_f32_e32 v106, v126, v106
	v_add_f32_e32 v118, v127, v106
	v_cvt_pk_bf16_f32 v154, v122, v123
	v_cvt_pk_bf16_f32 v155, v124, v125
	ds_read_b64_tr_b16 v[106:107], v209 offset:29696
	ds_read_b64_tr_b16 v[108:109], v209 offset:30208
	v_mfma_f32_32x32x16_bf16 v[66:81], v[102:105], v[138:141], v[66:81]
	v_add_f32_e32 v118, v128, v118
	v_add_f32_e32 v118, v129, v118
	v_add_f32_e32 v118, v50, v118
	v_add_f32_e32 v118, v51, v118
	v_cvt_pk_bf16_f32 v156, v126, v127
	v_cvt_pk_bf16_f32 v157, v128, v129
	ds_read_b64_tr_b16 v[102:103], v209 offset:26624
	ds_read_b64_tr_b16 v[104:105], v209 offset:27136
	v_mfma_f32_32x32x16_bf16 v[82:97], v[98:101], v[134:137], v[82:97]
	v_add_f32_e32 v118, v52, v118
	v_add_f32_e32 v118, v53, v118
	v_add_f32_e32 v118, v54, v118
	v_add_f32_e32 v118, v55, v118
	v_cvt_pk_bf16_f32 v150, v50, v51
	v_cvt_pk_bf16_f32 v151, v52, v53
	ds_read_b64_tr_b16 v[98:99], v209 offset:30720
	ds_read_b64_tr_b16 v[100:101], v209 offset:31232
	v_mfma_f32_32x32x16_bf16 v[66:81], v[170:173], v[134:137], v[66:81]
	v_add_f32_e32 v50, v56, v118
	v_add_f32_e32 v50, v57, v50
	v_add_f32_e32 v50, v58, v50
	v_add_f32_e32 v50, v59, v50
	v_cvt_pk_bf16_f32 v152, v54, v55
	v_cvt_pk_bf16_f32 v153, v56, v57
	ds_read_b64_tr_b16 v[54:55], v209 offset:27648
	ds_read_b64_tr_b16 v[56:57], v209 offset:28160
	v_mfma_f32_32x32x16_bf16 v[82:97], v[174:177], v[130:133], v[82:97]
	v_add_f32_e32 v50, v60, v50
	v_add_f32_e32 v50, v61, v50
	v_add_f32_e32 v50, v62, v50
	v_add_f32_e32 v118, v63, v50
	v_cvt_pk_bf16_f32 v146, v58, v59
	v_cvt_pk_bf16_f32 v147, v60, v61
	ds_read_b64_tr_b16 v[50:51], v209 offset:31744
	ds_read_b64_tr_b16 v[52:53], v209 offset:32256
	v_mfma_f32_32x32x16_bf16 v[66:81], v[166:169], v[130:133], v[66:81]
	v_add_f32_e32 v58, v64, v118
	v_add_f32_e32 v58, v65, v58
	v_add_f32_e32 v58, 0, v58
	v_cvt_pk_bf16_f32 v148, v62, v63
	v_cvt_pk_bf16_f32 v149, v64, v65
	s_cmp_lg_u32 0, -1
	s_cselect_b32 s15, 0, 0
	v_add_f32_e32 v118, v182, v58
	v_lshl_add_u64 v[58:59], v[194:195], 0, s[36:37]
	s_add_i32 s15, s15, s69
	s_add_i32 s15, s15, 0xa000
	s_mov_b32 s18, m0
	s_mov_b32 m0, s15
	s_nop 0
	global_load_lds_dwordx4 v[58:59], off
	s_mov_b32 m0, s18
	v_max_f32_e32 v58, v83, v83
	v_max_f32_e32 v59, v82, v82
	v_max_f32_e32 v58, v59, v58
	v_max3_f32 v59, v84, v85, v67
	v_max3_f32 v58, v58, v66, v68
	v_max3_f32 v58, v58, v69, v86
	v_max3_f32 v59, v59, v88, v89
	v_max3_f32 v58, v58, v87, v70
	v_max3_f32 v59, v59, v72, v73
	v_max3_f32 v58, v58, v71, v90
	v_max3_f32 v59, v59, v92, v93
	v_max3_f32 v58, v58, v91, v74
	v_max3_f32 v59, v59, v76, v77
	v_max3_f32 v58, v58, v75, v94
	v_max3_f32 v59, v59, v96, v97
	v_max3_f32 v58, v58, v95, v78
	v_max3_f32 v59, v59, v80, v81
	v_max3_f32 v58, v58, v79, v59
	v_mov_b32_e32 v59, v58
	s_nop 1
	v_permlane32_swap_b32_e32 v58, v59
	v_max_f32_e32 v59, v59, v59
	v_max_f32_e32 v58, v58, v58
	v_max_f32_e32 v58, v58, v59
	v_cmp_lt_f32_e32 vcc, s83, v58
	s_cmp_lg_u64 vcc, 0
	s_cselect_b64 s[60:61], -1, 0
	s_cbranch_vccnz .LBB0_1005

; __device__ __forceinline__ void kmask(f32x16&p0,f32x16&p1,int rem,int hi){
;   const float NEG=-INFINITY;
;   #pragma unroll
;   for(int r=0;r<16;++r){int kv=4*hi+(r&3)+8*(r>>2); if(kv>=rem)p0[r]=NEG; if(kv+32>=rem)p1[r]=NEG;}
; }
.LBB0_901:
	ds_read_b64_tr_b16 v[62:63], v209 offset:32768
	ds_read_b64_tr_b16 v[64:65], v209 offset:33280
	v_mfma_f32_32x32x16_bf16 v[34:49], v[114:117], v[142:145], v[34:49]
	v_add_f32_e32 v50, v82, v83
	v_add_f32_e32 v50, v84, v50
	v_add_f32_e32 v50, v85, v50
	v_add_f32_e32 v50, v86, v50
	v_add_f32_e32 v50, v87, v50
	v_cvt_pk_bf16_f32 v158, v82, v83
	v_cvt_pk_bf16_f32 v159, v84, v85
	ds_read_b64_tr_b16 v[102:103], v209 offset:36864
	ds_read_b64_tr_b16 v[104:105], v209 offset:37376
	v_add_f32_e32 v50, v88, v50
	v_add_f32_e32 v50, v89, v50
	v_add_f32_e32 v50, v90, v50
	v_add_f32_e32 v50, v91, v50
	v_cvt_pk_bf16_f32 v160, v86, v87
	v_cvt_pk_bf16_f32 v161, v88, v89
	ds_read_b64_tr_b16 v[98:99], v209 offset:33792
	ds_read_b64_tr_b16 v[100:101], v209 offset:34304
	v_mfma_f32_32x32x16_bf16 v[34:49], v[110:113], v[138:141], v[34:49]
	v_add_f32_e32 v50, v92, v50
	v_add_f32_e32 v50, v93, v50
	v_add_f32_e32 v50, v94, v50
	v_add_f32_e32 v50, v95, v50
	v_cvt_pk_bf16_f32 v154, v90, v91
	v_cvt_pk_bf16_f32 v155, v92, v93
	ds_read_b64_tr_b16 v[90:91], v209 offset:37888
	ds_read_b64_tr_b16 v[92:93], v209 offset:38400
	v_add_f32_e32 v50, v96, v50
	v_add_f32_e32 v50, v97, v50
	v_add_f32_e32 v50, v66, v50
	v_add_f32_e32 v50, v67, v50
	v_cvt_pk_bf16_f32 v156, v94, v95
	v_cvt_pk_bf16_f32 v157, v96, v97
	ds_read_b64_tr_b16 v[86:87], v209 offset:34816
	ds_read_b64_tr_b16 v[88:89], v209 offset:35328
	v_mfma_f32_32x32x16_bf16 v[34:49], v[106:109], v[134:137], v[34:49]
	v_add_f32_e32 v50, v68, v50
	v_add_f32_e32 v50, v69, v50
	v_add_f32_e32 v50, v70, v50
	v_add_f32_e32 v50, v71, v50
	v_cvt_pk_bf16_f32 v150, v66, v67
	v_cvt_pk_bf16_f32 v151, v68, v69
	ds_read_b64_tr_b16 v[82:83], v209 offset:38912
	ds_read_b64_tr_b16 v[84:85], v209 offset:39424
	v_add_f32_e32 v50, v72, v50
	v_add_f32_e32 v50, v73, v50
	v_add_f32_e32 v50, v74, v50
	v_add_f32_e32 v50, v75, v50
	v_cvt_pk_bf16_f32 v152, v70, v71
	v_cvt_pk_bf16_f32 v153, v72, v73
	ds_read_b64_tr_b16 v[70:71], v209 offset:35840
	ds_read_b64_tr_b16 v[72:73], v209 offset:36352
	v_mfma_f32_32x32x16_bf16 v[34:49], v[58:61], v[130:133], v[34:49]
	v_add_f32_e32 v50, v76, v50
	v_add_f32_e32 v50, v77, v50
	v_add_f32_e32 v50, v78, v50
	v_add_f32_e32 v50, v79, v50
	v_cvt_pk_bf16_f32 v146, v74, v75
	v_cvt_pk_bf16_f32 v147, v76, v77
	ds_read_b64_tr_b16 v[66:67], v209 offset:39936
	ds_read_b64_tr_b16 v[68:69], v209 offset:40448
	s_nop 3
	v_add_f32_e32 v42, v80, v50
	v_add_f32_e32 v42, v81, v42
	v_add_f32_e32 v42, 0, v42
	v_cvt_pk_bf16_f32 v148, v78, v79
	v_cvt_pk_bf16_f32 v149, v80, v81
	v_max_f32_e32 v44, v37, v37
	v_max_f32_e32 v45, v36, v36
	v_add_f32_e32 v74, v118, v42
	v_mov_b32_e32 v42, 0xff800000
	v_max_f32_e32 v44, v45, v44
	v_max3_f32 v43, v34, v35, v42
	v_max3_f32 v44, v44, v42, v40
	v_max3_f32 v43, v43, v38, v39
	v_max3_f32 v44, v44, v41, v42
	v_max3_f32 v43, v43, v42, v44
	v_mov_b32_e32 v44, v43
	s_nop 1
	v_permlane32_swap_b32_e32 v43, v44
	v_max_f32_e32 v44, v44, v44
	v_max_f32_e32 v43, v43, v43
	v_max_f32_e32 v43, v43, v44
	v_cmp_lt_f32_e32 vcc, s83, v43
	s_cmp_lg_u64 vcc, 0
	s_cselect_b64 s[60:61], -1, 0
	s_cbranch_vccnz .LBB0_1008

.LBB0_919:
	v_add_u32_e32 v183, s18, v208
	ds_read_b64_tr_b16 v[178:179], v183 offset:24576
	ds_read_b64_tr_b16 v[180:181], v183 offset:25088
	v_mfma_f32_32x32x16_bf16 v[98:113], v[82:85], v[142:145], v[34:49]
	v_add_f32_e32 v86, v66, v67
	v_add_f32_e32 v86, v68, v86
	v_add_f32_e32 v86, v69, v86
	v_add_f32_e32 v86, v70, v86
	v_add_f32_e32 v86, v71, v86
	v_cvt_pk_bf16_f32 v158, v66, v67
	v_cvt_pk_bf16_f32 v159, v68, v69
	ds_read_b64_tr_b16 v[174:175], v183 offset:28672
	ds_read_b64_tr_b16 v[176:177], v183 offset:29184
	v_add_f32_e32 v66, v72, v86
	v_mfma_f32_32x32x16_bf16 v[82:97], v[170:173], v[142:145], v[34:49]
	v_add_f32_e32 v66, v73, v66
	v_add_f32_e32 v66, v74, v66
	v_add_f32_e32 v66, v75, v66
	v_cvt_pk_bf16_f32 v160, v70, v71
	v_cvt_pk_bf16_f32 v161, v72, v73
	ds_read_b64_tr_b16 v[170:171], v183 offset:25600
	ds_read_b64_tr_b16 v[172:173], v183 offset:26112
	v_mfma_f32_32x32x16_bf16 v[98:113], v[166:169], v[138:141], v[98:113]
	v_add_f32_e32 v66, v76, v66
	v_add_f32_e32 v66, v77, v66
	v_add_f32_e32 v66, v78, v66
	v_add_f32_e32 v66, v79, v66
	v_cvt_pk_bf16_f32 v154, v74, v75
	v_cvt_pk_bf16_f32 v155, v76, v77
	ds_read_b64_tr_b16 v[74:75], v183 offset:29696
	ds_read_b64_tr_b16 v[76:77], v183 offset:30208
	v_mfma_f32_32x32x16_bf16 v[82:97], v[162:165], v[138:141], v[82:97]
	v_add_f32_e32 v66, v80, v66
	v_add_f32_e32 v66, v81, v66
	v_add_f32_e32 v66, v50, v66
	v_add_f32_e32 v66, v51, v66
	v_cvt_pk_bf16_f32 v156, v78, v79
	v_cvt_pk_bf16_f32 v157, v80, v81
	ds_read_b64_tr_b16 v[70:71], v183 offset:26624
	ds_read_b64_tr_b16 v[72:73], v183 offset:27136
	v_mfma_f32_32x32x16_bf16 v[98:113], v[126:129], v[134:137], v[98:113]
	v_add_f32_e32 v66, v52, v66
	v_add_f32_e32 v66, v53, v66
	v_add_f32_e32 v66, v54, v66
	v_add_f32_e32 v78, v55, v66
	v_cvt_pk_bf16_f32 v150, v50, v51
	v_cvt_pk_bf16_f32 v151, v52, v53
	ds_read_b64_tr_b16 v[66:67], v183 offset:30720
	ds_read_b64_tr_b16 v[68:69], v183 offset:31232
	v_mfma_f32_32x32x16_bf16 v[82:97], v[122:125], v[134:137], v[82:97]
	v_add_f32_e32 v50, v56, v78
	v_add_f32_e32 v50, v57, v50
	v_add_f32_e32 v50, v58, v50
	v_add_f32_e32 v50, v59, v50
	v_cvt_pk_bf16_f32 v152, v54, v55
	v_cvt_pk_bf16_f32 v153, v56, v57
	ds_read_b64_tr_b16 v[54:55], v183 offset:27648
	ds_read_b64_tr_b16 v[56:57], v183 offset:28160
	v_mfma_f32_32x32x16_bf16 v[98:113], v[118:121], v[130:133], v[98:113]
	v_add_f32_e32 v50, v60, v50
	v_add_f32_e32 v50, v61, v50
	v_add_f32_e32 v50, v62, v50
	v_add_f32_e32 v78, v63, v50
	v_cvt_pk_bf16_f32 v146, v58, v59
	v_cvt_pk_bf16_f32 v147, v60, v61
	ds_read_b64_tr_b16 v[50:51], v183 offset:31744
	ds_read_b64_tr_b16 v[52:53], v183 offset:32256
	v_mfma_f32_32x32x16_bf16 v[82:97], v[114:117], v[130:133], v[82:97]
	v_add_f32_e32 v58, v64, v78
	v_add_f32_e32 v58, v65, v58
	v_add_f32_e32 v60, 0, v58
	v_cvt_pk_bf16_f32 v148, v62, v63
	v_cvt_pk_bf16_f32 v149, v64, v65
	v_lshl_add_u64 v[58:59], v[196:197], 0, s[30:31]
	s_add_i32 s15, s64, s93
	s_mov_b32 s18, m0
	s_mov_b32 m0, s15
	s_nop 0
	global_load_lds_dwordx4 v[58:59], off
	s_mov_b32 m0, s18
	v_lshl_add_u64 v[58:59], v[188:189], 0, s[26:27]
	s_add_i32 s15, s95, s69
	s_mov_b32 s18, m0
	s_mov_b32 m0, s15
	s_nop 0
	global_load_lds_dwordx4 v[58:59], off
	s_mov_b32 m0, s18
	v_max_f32_e32 v58, v99, v99
	v_max_f32_e32 v59, v98, v98
	v_max_f32_e32 v58, v59, v58
	v_max3_f32 v59, v100, v101, v83
	v_max3_f32 v58, v58, v82, v84
	v_max3_f32 v58, v58, v85, v102
	v_max3_f32 v59, v59, v104, v105
	v_max3_f32 v58, v58, v103, v86
	v_max3_f32 v59, v59, v88, v89
	v_max3_f32 v58, v58, v87, v106
	v_max3_f32 v59, v59, v108, v109
	v_max3_f32 v58, v58, v107, v90
	v_max3_f32 v59, v59, v92, v93
	v_max3_f32 v58, v58, v91, v110
	v_max3_f32 v59, v59, v112, v113
	v_max3_f32 v58, v58, v111, v94
	v_max3_f32 v59, v59, v96, v97
	v_max3_f32 v58, v58, v95, v59
	v_mov_b32_e32 v59, v58
	s_nop 1
	v_permlane32_swap_b32_e32 v58, v59
	v_max_f32_e32 v59, v59, v59
	v_max_f32_e32 v58, v58, v58
	v_max_f32_e32 v58, v58, v59
	v_cmp_lt_f32_e32 vcc, s83, v58
	s_cmp_lg_u64 vcc, 0
	v_add_f32_e32 v192, v182, v60
	s_cselect_b64 s[60:61], -1, 0
	s_cbranch_vccnz .LBB0_927

.LBB0_922:
	s_add_i32 s15, s95, 0x2000
	s_cmpk_lg_i32 s95, 0x4000
	s_cselect_b32 s65, s15, 0
	v_add_u32_e32 v203, s64, v208
	ds_read_b64_tr_b16 v[126:127], v203 offset:24576
	ds_read_b64_tr_b16 v[128:129], v203 offset:25088
	v_mfma_f32_32x32x16_bf16 v[66:81], v[58:61], v[142:145], v[34:49]
	v_add_f32_e32 v50, v98, v99
	v_add_f32_e32 v50, v100, v50
	v_add_f32_e32 v50, v101, v50
	v_add_f32_e32 v50, v102, v50
	v_add_f32_e32 v50, v103, v50
	v_cvt_pk_bf16_f32 v158, v98, v99
	v_cvt_pk_bf16_f32 v159, v100, v101
	ds_read_b64_tr_b16 v[122:123], v203 offset:28672
	ds_read_b64_tr_b16 v[124:125], v203 offset:29184
	v_add_f32_e32 v50, v104, v50
	v_add_f32_e32 v50, v105, v50
	v_add_f32_e32 v50, v106, v50
	v_add_f32_e32 v98, v107, v50
	v_mfma_f32_32x32x16_bf16 v[50:65], v[114:117], v[142:145], v[34:49]
	v_cvt_pk_bf16_f32 v160, v102, v103
	v_cvt_pk_bf16_f32 v161, v104, v105
	ds_read_b64_tr_b16 v[118:119], v203 offset:25600
	ds_read_b64_tr_b16 v[120:121], v203 offset:26112
	v_mfma_f32_32x32x16_bf16 v[66:81], v[182:185], v[138:141], v[66:81]
	v_add_f32_e32 v98, v108, v98
	v_add_f32_e32 v98, v109, v98
	v_add_f32_e32 v98, v110, v98
	v_add_f32_e32 v98, v111, v98
	v_cvt_pk_bf16_f32 v154, v106, v107
	v_cvt_pk_bf16_f32 v155, v108, v109
	ds_read_b64_tr_b16 v[114:115], v203 offset:29696
	ds_read_b64_tr_b16 v[116:117], v203 offset:30208
	v_mfma_f32_32x32x16_bf16 v[50:65], v[174:177], v[138:141], v[50:65]
	v_add_f32_e32 v98, v112, v98
	v_add_f32_e32 v98, v113, v98
	v_add_f32_e32 v98, v82, v98
	v_add_f32_e32 v98, v83, v98
	v_cvt_pk_bf16_f32 v156, v110, v111
	v_cvt_pk_bf16_f32 v157, v112, v113
	ds_read_b64_tr_b16 v[106:107], v203 offset:26624
	ds_read_b64_tr_b16 v[108:109], v203 offset:27136
	v_mfma_f32_32x32x16_bf16 v[66:81], v[178:181], v[134:137], v[66:81]
	v_add_f32_e32 v98, v84, v98
	v_add_f32_e32 v98, v85, v98
	v_add_f32_e32 v98, v86, v98
	v_add_f32_e32 v98, v87, v98
	v_cvt_pk_bf16_f32 v150, v82, v83
	v_cvt_pk_bf16_f32 v151, v84, v85
	ds_read_b64_tr_b16 v[102:103], v203 offset:30720
	ds_read_b64_tr_b16 v[104:105], v203 offset:31232
	v_mfma_f32_32x32x16_bf16 v[50:65], v[166:169], v[134:137], v[50:65]
	v_add_f32_e32 v82, v88, v98
	v_add_f32_e32 v82, v89, v82
	v_add_f32_e32 v82, v90, v82
	v_add_f32_e32 v82, v91, v82
	v_cvt_pk_bf16_f32 v152, v86, v87
	v_cvt_pk_bf16_f32 v153, v88, v89
	ds_read_b64_tr_b16 v[98:99], v203 offset:27648
	ds_read_b64_tr_b16 v[100:101], v203 offset:28160
	v_mfma_f32_32x32x16_bf16 v[66:81], v[170:173], v[130:133], v[66:81]
	v_add_f32_e32 v82, v92, v82
	v_add_f32_e32 v82, v93, v82
	v_add_f32_e32 v82, v94, v82
	v_add_f32_e32 v82, v95, v82
	v_cvt_pk_bf16_f32 v146, v90, v91
	v_cvt_pk_bf16_f32 v147, v92, v93
	ds_read_b64_tr_b16 v[86:87], v203 offset:31744
	ds_read_b64_tr_b16 v[88:89], v203 offset:32256
	v_mfma_f32_32x32x16_bf16 v[50:65], v[162:165], v[130:133], v[50:65]
	v_add_f32_e32 v82, v96, v82
	v_add_f32_e32 v82, v97, v82
	v_add_f32_e32 v84, 0, v82
	v_cvt_pk_bf16_f32 v148, v94, v95
	v_cvt_pk_bf16_f32 v149, v96, v97
	v_lshl_add_u64 v[82:83], v[196:197], 0, s[34:35]
	s_add_i32 s15, s95, s93
	s_mov_b32 s18, m0
	s_mov_b32 m0, s15
	s_nop 0
	global_load_lds_dwordx4 v[82:83], off
	s_mov_b32 m0, s18
	v_max_f32_e32 v82, v67, v67
	v_max_f32_e32 v83, v66, v66
	v_max_f32_e32 v82, v83, v82
	s_nop 1
	v_max3_f32 v83, v68, v69, v51
	v_max3_f32 v82, v82, v50, v52
	v_max3_f32 v82, v82, v53, v70
	v_max3_f32 v83, v83, v72, v73
	v_max3_f32 v82, v82, v71, v54
	v_max3_f32 v83, v83, v56, v57
	v_max3_f32 v82, v82, v55, v74
	v_max3_f32 v83, v83, v76, v77
	v_max3_f32 v82, v82, v75, v58
	v_max3_f32 v83, v83, v60, v61
	v_max3_f32 v82, v82, v59, v78
	v_max3_f32 v83, v83, v80, v81
	v_max3_f32 v82, v82, v79, v62
	v_max3_f32 v83, v83, v64, v65
	v_max3_f32 v82, v82, v63, v83
	v_mov_b32_e32 v83, v82
	s_nop 1
	v_permlane32_swap_b32_e32 v82, v83
	v_max_f32_e32 v83, v83, v83
	v_max_f32_e32 v82, v82, v82
	v_max_f32_e32 v82, v82, v83
	v_lshl_add_u64 v[188:189], v[188:189], 0, s[28:29]
	s_add_i32 s15, s65, s69
	s_mov_b32 s18, m0
	s_mov_b32 m0, s15
	s_nop 0
	global_load_lds_dwordx4 v[188:189], off
	s_mov_b32 m0, s18
	v_cmp_lt_f32_e32 vcc, s83, v82
	s_cmp_lg_u64 vcc, 0
	v_add_f32_e32 v182, v192, v84
	s_cselect_b64 s[60:61], -1, 0
	s_cbranch_vccnz .LBB0_930

.LBB0_936:
	ds_read_b64_tr_b16 v[166:167], v208 offset:32768
	ds_read_b64_tr_b16 v[168:169], v208 offset:33280
	v_mfma_f32_32x32x16_bf16 v[114:129], v[58:61], v[142:145], v[34:49]
	v_add_f32_e32 v50, v98, v99
	v_add_f32_e32 v50, v100, v50
	v_add_f32_e32 v50, v101, v50
	v_add_f32_e32 v50, v102, v50
	v_add_f32_e32 v50, v103, v50
	v_cvt_pk_bf16_f32 v158, v98, v99
	v_cvt_pk_bf16_f32 v159, v100, v101
	ds_read_b64_tr_b16 v[162:163], v208 offset:36864
	ds_read_b64_tr_b16 v[164:165], v208 offset:37376
	v_add_f32_e32 v50, v104, v50
	v_add_f32_e32 v50, v105, v50
	v_add_f32_e32 v50, v106, v50
	v_add_f32_e32 v66, v107, v50
	v_mfma_f32_32x32x16_bf16 v[50:65], v[182:185], v[142:145], v[34:49]
	v_cvt_pk_bf16_f32 v160, v102, v103
	v_cvt_pk_bf16_f32 v161, v104, v105
	ds_read_b64_tr_b16 v[102:103], v208 offset:33792
	ds_read_b64_tr_b16 v[104:105], v208 offset:34304
	v_mfma_f32_32x32x16_bf16 v[114:129], v[186:189], v[138:141], v[114:129]
	v_add_f32_e32 v66, v108, v66
	v_add_f32_e32 v66, v109, v66
	v_add_f32_e32 v66, v110, v66
	v_add_f32_e32 v66, v111, v66
	v_cvt_pk_bf16_f32 v154, v106, v107
	v_cvt_pk_bf16_f32 v155, v108, v109
	ds_read_b64_tr_b16 v[98:99], v208 offset:37888
	ds_read_b64_tr_b16 v[100:101], v208 offset:38400
	v_mfma_f32_32x32x16_bf16 v[50:65], v[78:81], v[138:141], v[50:65]
	v_add_f32_e32 v66, v112, v66
	v_add_f32_e32 v66, v113, v66
	v_add_f32_e32 v66, v82, v66
	v_add_f32_e32 v66, v83, v66
	v_cvt_pk_bf16_f32 v156, v110, v111
	v_cvt_pk_bf16_f32 v157, v112, v113
	ds_read_b64_tr_b16 v[78:79], v208 offset:34816
	ds_read_b64_tr_b16 v[80:81], v208 offset:35328
	v_mfma_f32_32x32x16_bf16 v[114:129], v[74:77], v[134:137], v[114:129]
	v_add_f32_e32 v66, v84, v66
	v_add_f32_e32 v66, v85, v66
	v_add_f32_e32 v66, v86, v66
	v_add_f32_e32 v66, v87, v66
	v_cvt_pk_bf16_f32 v150, v82, v83
	v_cvt_pk_bf16_f32 v151, v84, v85
	ds_read_b64_tr_b16 v[74:75], v208 offset:38912
	ds_read_b64_tr_b16 v[76:77], v208 offset:39424
	v_mfma_f32_32x32x16_bf16 v[50:65], v[174:177], v[134:137], v[50:65]
	v_add_f32_e32 v66, v88, v66
	v_add_f32_e32 v66, v89, v66
	v_add_f32_e32 v66, v90, v66
	v_add_f32_e32 v66, v91, v66
	v_cvt_pk_bf16_f32 v152, v86, v87
	v_cvt_pk_bf16_f32 v153, v88, v89
	ds_read_b64_tr_b16 v[70:71], v208 offset:35840
	ds_read_b64_tr_b16 v[72:73], v208 offset:36352
	v_mfma_f32_32x32x16_bf16 v[114:129], v[178:181], v[130:133], v[114:129]
	v_add_f32_e32 v66, v92, v66
	v_add_f32_e32 v66, v93, v66
	v_add_f32_e32 v66, v94, v66
	v_add_f32_e32 v82, v95, v66
	v_cvt_pk_bf16_f32 v146, v90, v91
	v_cvt_pk_bf16_f32 v147, v92, v93
	ds_read_b64_tr_b16 v[66:67], v208 offset:39936
	ds_read_b64_tr_b16 v[68:69], v208 offset:40448
	v_mfma_f32_32x32x16_bf16 v[50:65], v[170:173], v[130:133], v[50:65]
	v_add_f32_e32 v82, v96, v82
	v_add_f32_e32 v82, v97, v82
	v_add_f32_e32 v82, 0, v82
	v_cvt_pk_bf16_f32 v148, v94, v95
	v_cvt_pk_bf16_f32 v149, v96, v97
	s_nop 0
	v_add_f32_e32 v182, v196, v82
	v_lshl_add_u64 v[82:83], v[194:195], 0, s[46:47]
	s_mov_b32 s15, m0
	s_mov_b32 m0, s69
	s_nop 0
	global_load_lds_dwordx4 v[82:83], off
	s_mov_b32 m0, s15
	v_max_f32_e32 v82, v115, v115
	v_max_f32_e32 v83, v114, v114
	v_max_f32_e32 v82, v83, v82
	s_nop 0
	v_max3_f32 v83, v116, v117, v51
	v_max3_f32 v82, v82, v50, v52
	v_max3_f32 v82, v82, v53, v118
	v_max3_f32 v83, v83, v120, v121
	v_max3_f32 v82, v82, v119, v54
	v_max3_f32 v83, v83, v56, v57
	v_max3_f32 v82, v82, v55, v122
	v_max3_f32 v83, v83, v124, v125
	v_max3_f32 v82, v82, v123, v58
	v_max3_f32 v83, v83, v60, v61
	v_max3_f32 v82, v82, v59, v126
	v_max3_f32 v83, v83, v128, v129
	v_max3_f32 v82, v82, v127, v62
	v_max3_f32 v83, v83, v64, v65
	v_max3_f32 v82, v82, v63, v83
	v_mov_b32_e32 v83, v82
	s_nop 1
	v_permlane32_swap_b32_e32 v82, v83
	v_max_f32_e32 v83, v83, v83
	v_max_f32_e32 v82, v82, v82
	v_max_f32_e32 v82, v82, v83
	v_cmp_lt_f32_e32 vcc, s83, v82
	s_cmp_lg_u64 vcc, 0
	s_cselect_b64 s[60:61], -1, 0
	s_cbranch_vccnz .LBB0_1014

.LBB0_939:
	ds_read_b64_tr_b16 v[162:163], v208 offset:40960
	ds_read_b64_tr_b16 v[164:165], v208 offset:41472
	v_mfma_f32_32x32x16_bf16 v[82:97], v[110:113], v[142:145], v[34:49]
	v_add_f32_e32 v66, v114, v115
	v_add_f32_e32 v66, v116, v66
	v_add_f32_e32 v66, v117, v66
	v_add_f32_e32 v66, v118, v66
	v_add_f32_e32 v66, v119, v66
	v_cvt_pk_bf16_f32 v158, v114, v115
	v_cvt_pk_bf16_f32 v159, v116, v117
	ds_read_b64_tr_b16 v[114:115], v208 offset:45056
	ds_read_b64_tr_b16 v[116:117], v208 offset:45568
	v_add_f32_e32 v66, v120, v66
	v_add_f32_e32 v66, v121, v66
	v_add_f32_e32 v66, v122, v66
	v_add_f32_e32 v146, v123, v66
	v_mfma_f32_32x32x16_bf16 v[66:81], v[106:109], v[142:145], v[34:49]
	v_cvt_pk_bf16_f32 v160, v118, v119
	v_cvt_pk_bf16_f32 v161, v120, v121
	ds_read_b64_tr_b16 v[110:111], v208 offset:41984
	ds_read_b64_tr_b16 v[112:113], v208 offset:42496
	v_mfma_f32_32x32x16_bf16 v[82:97], v[178:181], v[138:141], v[82:97]
	v_add_f32_e32 v106, v124, v146
	v_add_f32_e32 v106, v125, v106
	v_add_f32_e32 v106, v126, v106
	v_add_f32_e32 v118, v127, v106
	v_cvt_pk_bf16_f32 v154, v122, v123
	v_cvt_pk_bf16_f32 v155, v124, v125
	ds_read_b64_tr_b16 v[106:107], v208 offset:46080
	ds_read_b64_tr_b16 v[108:109], v208 offset:46592
	v_mfma_f32_32x32x16_bf16 v[66:81], v[102:105], v[138:141], v[66:81]
	v_add_f32_e32 v118, v128, v118
	v_add_f32_e32 v118, v129, v118
	v_add_f32_e32 v118, v50, v118
	v_add_f32_e32 v118, v51, v118
	v_cvt_pk_bf16_f32 v156, v126, v127
	v_cvt_pk_bf16_f32 v157, v128, v129
	ds_read_b64_tr_b16 v[102:103], v208 offset:43008
	ds_read_b64_tr_b16 v[104:105], v208 offset:43520
	v_mfma_f32_32x32x16_bf16 v[82:97], v[98:101], v[134:137], v[82:97]
	v_add_f32_e32 v118, v52, v118
	v_add_f32_e32 v118, v53, v118
	v_add_f32_e32 v118, v54, v118
	v_add_f32_e32 v118, v55, v118
	v_cvt_pk_bf16_f32 v150, v50, v51
	v_cvt_pk_bf16_f32 v151, v52, v53
	ds_read_b64_tr_b16 v[98:99], v208 offset:47104
	ds_read_b64_tr_b16 v[100:101], v208 offset:47616
	v_mfma_f32_32x32x16_bf16 v[66:81], v[170:173], v[134:137], v[66:81]
	v_add_f32_e32 v50, v56, v118
	v_add_f32_e32 v50, v57, v50
	v_add_f32_e32 v50, v58, v50
	v_add_f32_e32 v50, v59, v50
	v_cvt_pk_bf16_f32 v152, v54, v55
	v_cvt_pk_bf16_f32 v153, v56, v57
	ds_read_b64_tr_b16 v[54:55], v208 offset:44032
	ds_read_b64_tr_b16 v[56:57], v208 offset:44544
	v_mfma_f32_32x32x16_bf16 v[82:97], v[174:177], v[130:133], v[82:97]
	v_add_f32_e32 v50, v60, v50
	v_add_f32_e32 v50, v61, v50
	v_add_f32_e32 v50, v62, v50
	v_add_f32_e32 v118, v63, v50
	v_cvt_pk_bf16_f32 v146, v58, v59
	v_cvt_pk_bf16_f32 v147, v60, v61
	ds_read_b64_tr_b16 v[50:51], v208 offset:48128
	ds_read_b64_tr_b16 v[52:53], v208 offset:48640
	v_mfma_f32_32x32x16_bf16 v[66:81], v[166:169], v[130:133], v[66:81]
	v_add_f32_e32 v58, v64, v118
	v_add_f32_e32 v58, v65, v58
	v_add_f32_e32 v58, 0, v58
	v_cvt_pk_bf16_f32 v148, v62, v63
	v_cvt_pk_bf16_f32 v149, v64, v65
	s_cmp_lg_u32 0, -1
	s_cselect_b32 s15, 0, 0
	v_add_f32_e32 v118, v182, v58
	v_lshl_add_u64 v[58:59], v[194:195], 0, s[42:43]
	s_add_i32 s15, s15, s68
	s_add_i32 s15, s15, 0x8000
	s_mov_b32 s18, m0
	s_mov_b32 m0, s15
	s_nop 0
	global_load_lds_dwordx4 v[58:59], off
	s_mov_b32 m0, s18
	v_max_f32_e32 v58, v83, v83
	v_max_f32_e32 v59, v82, v82
	v_max_f32_e32 v58, v59, v58
	v_max3_f32 v59, v84, v85, v67
	v_max3_f32 v58, v58, v66, v68
	v_max3_f32 v58, v58, v69, v86
	v_max3_f32 v59, v59, v88, v89
	v_max3_f32 v58, v58, v87, v70
	v_max3_f32 v59, v59, v72, v73
	v_max3_f32 v58, v58, v71, v90
	v_max3_f32 v59, v59, v92, v93
	v_max3_f32 v58, v58, v91, v74
	v_max3_f32 v59, v59, v76, v77
	v_max3_f32 v58, v58, v75, v94
	v_max3_f32 v59, v59, v96, v97
	v_max3_f32 v58, v58, v95, v78
	v_max3_f32 v59, v59, v80, v81
	v_max3_f32 v58, v58, v79, v59
	v_mov_b32_e32 v59, v58
	s_nop 1
	v_permlane32_swap_b32_e32 v58, v59
	v_max_f32_e32 v59, v59, v59
	v_max_f32_e32 v58, v58, v58
	v_max_f32_e32 v58, v58, v59
	v_cmp_lt_f32_e32 vcc, s83, v58
	s_cmp_lg_u64 vcc, 0
	s_cselect_b64 s[60:61], -1, 0
	s_cbranch_vccnz .LBB0_1017

; __device__ __forceinline__ void kmask(f32x16&p0,f32x16&p1,int rem,int hi){
;   const float NEG=-INFINITY;
;   #pragma unroll
;   for(int r=0;r<16;++r){int kv=4*hi+(r&3)+8*(r>>2); if(kv>=rem)p0[r]=NEG; if(kv+32>=rem)p1[r]=NEG;}
; }
.LBB0_942:
	ds_read_b64_tr_b16 v[62:63], v208 offset:24576
	ds_read_b64_tr_b16 v[64:65], v208 offset:25088
	v_mfma_f32_32x32x16_bf16 v[34:49], v[114:117], v[142:145], v[34:49]
	v_add_f32_e32 v50, v82, v83
	v_add_f32_e32 v50, v84, v50
	v_add_f32_e32 v50, v85, v50
	v_add_f32_e32 v50, v86, v50
	v_add_f32_e32 v50, v87, v50
	v_cvt_pk_bf16_f32 v158, v82, v83
	v_cvt_pk_bf16_f32 v159, v84, v85
	ds_read_b64_tr_b16 v[102:103], v208 offset:28672
	ds_read_b64_tr_b16 v[104:105], v208 offset:29184
	v_add_f32_e32 v50, v88, v50
	v_add_f32_e32 v50, v89, v50
	v_add_f32_e32 v50, v90, v50
	v_add_f32_e32 v50, v91, v50
	v_cvt_pk_bf16_f32 v160, v86, v87
	v_cvt_pk_bf16_f32 v161, v88, v89
	ds_read_b64_tr_b16 v[98:99], v208 offset:25600
	ds_read_b64_tr_b16 v[100:101], v208 offset:26112
	v_mfma_f32_32x32x16_bf16 v[34:49], v[110:113], v[138:141], v[34:49]
	v_add_f32_e32 v50, v92, v50
	v_add_f32_e32 v50, v93, v50
	v_add_f32_e32 v50, v94, v50
	v_add_f32_e32 v50, v95, v50
	v_cvt_pk_bf16_f32 v154, v90, v91
	v_cvt_pk_bf16_f32 v155, v92, v93
	ds_read_b64_tr_b16 v[90:91], v208 offset:29696
	ds_read_b64_tr_b16 v[92:93], v208 offset:30208
	v_add_f32_e32 v50, v96, v50
	v_add_f32_e32 v50, v97, v50
	v_add_f32_e32 v50, v66, v50
	v_add_f32_e32 v50, v67, v50
	v_cvt_pk_bf16_f32 v156, v94, v95
	v_cvt_pk_bf16_f32 v157, v96, v97
	ds_read_b64_tr_b16 v[86:87], v208 offset:26624
	ds_read_b64_tr_b16 v[88:89], v208 offset:27136
	v_mfma_f32_32x32x16_bf16 v[34:49], v[106:109], v[134:137], v[34:49]
	v_add_f32_e32 v50, v68, v50
	v_add_f32_e32 v50, v69, v50
	v_add_f32_e32 v50, v70, v50
	v_add_f32_e32 v50, v71, v50
	v_cvt_pk_bf16_f32 v150, v66, v67
	v_cvt_pk_bf16_f32 v151, v68, v69
	ds_read_b64_tr_b16 v[82:83], v208 offset:30720
	ds_read_b64_tr_b16 v[84:85], v208 offset:31232
	v_add_f32_e32 v50, v72, v50
	v_add_f32_e32 v50, v73, v50
	v_add_f32_e32 v50, v74, v50
	v_add_f32_e32 v50, v75, v50
	v_cvt_pk_bf16_f32 v152, v70, v71
	v_cvt_pk_bf16_f32 v153, v72, v73
	ds_read_b64_tr_b16 v[70:71], v208 offset:27648
	ds_read_b64_tr_b16 v[72:73], v208 offset:28160
	v_mfma_f32_32x32x16_bf16 v[34:49], v[58:61], v[130:133], v[34:49]
	v_add_f32_e32 v50, v76, v50
	v_add_f32_e32 v50, v77, v50
	v_add_f32_e32 v50, v78, v50
	v_add_f32_e32 v50, v79, v50
	v_cvt_pk_bf16_f32 v146, v74, v75
	v_cvt_pk_bf16_f32 v147, v76, v77
	ds_read_b64_tr_b16 v[66:67], v208 offset:31744
	ds_read_b64_tr_b16 v[68:69], v208 offset:32256
	s_nop 3
	v_add_f32_e32 v42, v80, v50
	v_add_f32_e32 v42, v81, v42
	v_add_f32_e32 v42, 0, v42
	v_cvt_pk_bf16_f32 v148, v78, v79
	v_cvt_pk_bf16_f32 v149, v80, v81
	v_max_f32_e32 v44, v37, v37
	v_max_f32_e32 v45, v36, v36
	v_add_f32_e32 v74, v118, v42
	v_mov_b32_e32 v42, 0xff800000
	v_max_f32_e32 v44, v45, v44
	v_max3_f32 v43, v34, v35, v42
	v_max3_f32 v44, v44, v42, v40
	v_max3_f32 v43, v43, v38, v39
	v_max3_f32 v44, v44, v41, v42
	v_max3_f32 v43, v43, v42, v44
	v_mov_b32_e32 v44, v43
	s_nop 1
	v_permlane32_swap_b32_e32 v43, v44
	v_max_f32_e32 v44, v44, v44
	v_max_f32_e32 v43, v43, v43
	v_max_f32_e32 v43, v43, v44
	v_cmp_lt_f32_e32 vcc, s83, v43
	s_cmp_lg_u64 vcc, 0
	s_cselect_b64 s[60:61], -1, 0
	s_cbranch_vccnz .LBB0_1020

.LBB0_2477:
	v_add_u32_e32 v183, s18, v209
	ds_read_b64_tr_b16 v[178:179], v183 offset:24576
	ds_read_b64_tr_b16 v[180:181], v183 offset:25088
	v_mfma_f32_32x32x16_bf16 v[98:113], v[82:85], v[142:145], v[34:49]
	v_add_f32_e32 v86, v66, v67
	v_add_f32_e32 v86, v68, v86
	v_add_f32_e32 v86, v69, v86
	v_add_f32_e32 v86, v70, v86
	v_add_f32_e32 v86, v71, v86
	v_cvt_pk_bf16_f32 v158, v66, v67
	v_cvt_pk_bf16_f32 v159, v68, v69
	ds_read_b64_tr_b16 v[174:175], v183 offset:28672
	ds_read_b64_tr_b16 v[176:177], v183 offset:29184
	v_add_f32_e32 v66, v72, v86
	v_mfma_f32_32x32x16_bf16 v[82:97], v[170:173], v[142:145], v[34:49]
	v_add_f32_e32 v66, v73, v66
	v_add_f32_e32 v66, v74, v66
	v_add_f32_e32 v66, v75, v66
	v_cvt_pk_bf16_f32 v160, v70, v71
	v_cvt_pk_bf16_f32 v161, v72, v73
	ds_read_b64_tr_b16 v[170:171], v183 offset:25600
	ds_read_b64_tr_b16 v[172:173], v183 offset:26112
	v_mfma_f32_32x32x16_bf16 v[98:113], v[166:169], v[138:141], v[98:113]
	v_add_f32_e32 v66, v76, v66
	v_add_f32_e32 v66, v77, v66
	v_add_f32_e32 v66, v78, v66
	v_add_f32_e32 v66, v79, v66
	v_cvt_pk_bf16_f32 v154, v74, v75
	v_cvt_pk_bf16_f32 v155, v76, v77
	ds_read_b64_tr_b16 v[74:75], v183 offset:29696
	ds_read_b64_tr_b16 v[76:77], v183 offset:30208
	v_mfma_f32_32x32x16_bf16 v[82:97], v[162:165], v[138:141], v[82:97]
	v_add_f32_e32 v66, v80, v66
	v_add_f32_e32 v66, v81, v66
	v_add_f32_e32 v66, v50, v66
	v_add_f32_e32 v66, v51, v66
	v_cvt_pk_bf16_f32 v156, v78, v79
	v_cvt_pk_bf16_f32 v157, v80, v81
	ds_read_b64_tr_b16 v[70:71], v183 offset:26624
	ds_read_b64_tr_b16 v[72:73], v183 offset:27136
	v_mfma_f32_32x32x16_bf16 v[98:113], v[126:129], v[134:137], v[98:113]
	v_add_f32_e32 v66, v52, v66
	v_add_f32_e32 v66, v53, v66
	v_add_f32_e32 v66, v54, v66
	v_add_f32_e32 v78, v55, v66
	v_cvt_pk_bf16_f32 v150, v50, v51
	v_cvt_pk_bf16_f32 v151, v52, v53
	ds_read_b64_tr_b16 v[66:67], v183 offset:30720
	ds_read_b64_tr_b16 v[68:69], v183 offset:31232
	v_mfma_f32_32x32x16_bf16 v[82:97], v[122:125], v[134:137], v[82:97]
	v_add_f32_e32 v50, v56, v78
	v_add_f32_e32 v50, v57, v50
	v_add_f32_e32 v50, v58, v50
	v_add_f32_e32 v50, v59, v50
	v_cvt_pk_bf16_f32 v152, v54, v55
	v_cvt_pk_bf16_f32 v153, v56, v57
	ds_read_b64_tr_b16 v[54:55], v183 offset:27648
	ds_read_b64_tr_b16 v[56:57], v183 offset:28160
	v_mfma_f32_32x32x16_bf16 v[98:113], v[118:121], v[130:133], v[98:113]
	v_add_f32_e32 v50, v60, v50
	v_add_f32_e32 v50, v61, v50
	v_add_f32_e32 v50, v62, v50
	v_add_f32_e32 v78, v63, v50
	v_cvt_pk_bf16_f32 v146, v58, v59
	v_cvt_pk_bf16_f32 v147, v60, v61
	ds_read_b64_tr_b16 v[50:51], v183 offset:31744
	ds_read_b64_tr_b16 v[52:53], v183 offset:32256
	v_mfma_f32_32x32x16_bf16 v[82:97], v[114:117], v[130:133], v[82:97]
	v_add_f32_e32 v58, v64, v78
	v_add_f32_e32 v58, v65, v58
	v_add_f32_e32 v60, 0, v58
	v_cvt_pk_bf16_f32 v148, v62, v63
	v_cvt_pk_bf16_f32 v149, v64, v65
	v_lshl_add_u64 v[58:59], v[196:197], 0, s[30:31]
	s_add_i32 s15, s64, s94
	s_mov_b32 s18, m0
	s_mov_b32 m0, s15
	s_nop 0
	global_load_lds_dwordx4 v[58:59], off
	s_mov_b32 m0, s18
	v_lshl_add_u64 v[58:59], v[188:189], 0, s[26:27]
	s_add_i32 s15, s96, s93
	s_mov_b32 s18, m0
	s_mov_b32 m0, s15
	s_nop 0
	global_load_lds_dwordx4 v[58:59], off
	s_mov_b32 m0, s18
	v_max_f32_e32 v58, v99, v99
	v_max_f32_e32 v59, v98, v98
	v_max_f32_e32 v58, v59, v58
	v_max3_f32 v59, v100, v101, v83
	v_max3_f32 v58, v58, v82, v84
	v_max3_f32 v58, v58, v85, v102
	v_max3_f32 v59, v59, v104, v105
	v_max3_f32 v58, v58, v103, v86
	v_max3_f32 v59, v59, v88, v89
	v_max3_f32 v58, v58, v87, v106
	v_max3_f32 v59, v59, v108, v109
	v_max3_f32 v58, v58, v107, v90
	v_max3_f32 v59, v59, v92, v93
	v_max3_f32 v58, v58, v91, v110
	v_max3_f32 v59, v59, v112, v113
	v_max3_f32 v58, v58, v111, v94
	v_max3_f32 v59, v59, v96, v97
	v_max3_f32 v58, v58, v95, v59
	v_mov_b32_e32 v59, v58
	s_nop 1
	v_permlane32_swap_b32_e32 v58, v59
	v_max_f32_e32 v59, v59, v59
	v_max_f32_e32 v58, v58, v58
	v_max_f32_e32 v58, v58, v59
	v_cmp_lt_f32_e32 vcc, s82, v58
	s_cmp_lg_u64 vcc, 0
	v_add_f32_e32 v213, v182, v60
	s_cselect_b64 s[60:61], -1, 0
	s_cbranch_vccnz .LBB0_2485

.LBB0_2480:
	s_add_i32 s15, s96, 0x2000
	s_cmpk_lg_i32 s96, 0x4000
	s_cselect_b32 s65, s15, 0
	v_add_u32_e32 v214, s64, v209
	ds_read_b64_tr_b16 v[126:127], v214 offset:24576
	ds_read_b64_tr_b16 v[128:129], v214 offset:25088
	v_mfma_f32_32x32x16_bf16 v[66:81], v[58:61], v[142:145], v[34:49]
	v_add_f32_e32 v50, v98, v99
	v_add_f32_e32 v50, v100, v50
	v_add_f32_e32 v50, v101, v50
	v_add_f32_e32 v50, v102, v50
	v_add_f32_e32 v50, v103, v50
	v_cvt_pk_bf16_f32 v158, v98, v99
	v_cvt_pk_bf16_f32 v159, v100, v101
	ds_read_b64_tr_b16 v[122:123], v214 offset:28672
	ds_read_b64_tr_b16 v[124:125], v214 offset:29184
	v_add_f32_e32 v50, v104, v50
	v_add_f32_e32 v50, v105, v50
	v_add_f32_e32 v50, v106, v50
	v_add_f32_e32 v98, v107, v50
	v_mfma_f32_32x32x16_bf16 v[50:65], v[114:117], v[142:145], v[34:49]
	v_cvt_pk_bf16_f32 v160, v102, v103
	v_cvt_pk_bf16_f32 v161, v104, v105
	ds_read_b64_tr_b16 v[118:119], v214 offset:25600
	ds_read_b64_tr_b16 v[120:121], v214 offset:26112
	v_mfma_f32_32x32x16_bf16 v[66:81], v[182:185], v[138:141], v[66:81]
	v_add_f32_e32 v98, v108, v98
	v_add_f32_e32 v98, v109, v98
	v_add_f32_e32 v98, v110, v98
	v_add_f32_e32 v98, v111, v98
	v_cvt_pk_bf16_f32 v154, v106, v107
	v_cvt_pk_bf16_f32 v155, v108, v109
	ds_read_b64_tr_b16 v[114:115], v214 offset:29696
	ds_read_b64_tr_b16 v[116:117], v214 offset:30208
	v_mfma_f32_32x32x16_bf16 v[50:65], v[174:177], v[138:141], v[50:65]
	v_add_f32_e32 v98, v112, v98
	v_add_f32_e32 v98, v113, v98
	v_add_f32_e32 v98, v82, v98
	v_add_f32_e32 v98, v83, v98
	v_cvt_pk_bf16_f32 v156, v110, v111
	v_cvt_pk_bf16_f32 v157, v112, v113
	ds_read_b64_tr_b16 v[106:107], v214 offset:26624
	ds_read_b64_tr_b16 v[108:109], v214 offset:27136
	v_mfma_f32_32x32x16_bf16 v[66:81], v[178:181], v[134:137], v[66:81]
	v_add_f32_e32 v98, v84, v98
	v_add_f32_e32 v98, v85, v98
	v_add_f32_e32 v98, v86, v98
	v_add_f32_e32 v98, v87, v98
	v_cvt_pk_bf16_f32 v150, v82, v83
	v_cvt_pk_bf16_f32 v151, v84, v85
	ds_read_b64_tr_b16 v[102:103], v214 offset:30720
	ds_read_b64_tr_b16 v[104:105], v214 offset:31232
	v_mfma_f32_32x32x16_bf16 v[50:65], v[166:169], v[134:137], v[50:65]
	v_add_f32_e32 v82, v88, v98
	v_add_f32_e32 v82, v89, v82
	v_add_f32_e32 v82, v90, v82
	v_add_f32_e32 v82, v91, v82
	v_cvt_pk_bf16_f32 v152, v86, v87
	v_cvt_pk_bf16_f32 v153, v88, v89
	ds_read_b64_tr_b16 v[98:99], v214 offset:27648
	ds_read_b64_tr_b16 v[100:101], v214 offset:28160
	v_mfma_f32_32x32x16_bf16 v[66:81], v[170:173], v[130:133], v[66:81]
	v_add_f32_e32 v82, v92, v82
	v_add_f32_e32 v82, v93, v82
	v_add_f32_e32 v82, v94, v82
	v_add_f32_e32 v82, v95, v82
	v_cvt_pk_bf16_f32 v146, v90, v91
	v_cvt_pk_bf16_f32 v147, v92, v93
	ds_read_b64_tr_b16 v[86:87], v214 offset:31744
	ds_read_b64_tr_b16 v[88:89], v214 offset:32256
	v_mfma_f32_32x32x16_bf16 v[50:65], v[162:165], v[130:133], v[50:65]
	v_add_f32_e32 v82, v96, v82
	v_add_f32_e32 v82, v97, v82
	v_add_f32_e32 v84, 0, v82
	v_cvt_pk_bf16_f32 v148, v94, v95
	v_cvt_pk_bf16_f32 v149, v96, v97
	v_lshl_add_u64 v[82:83], v[196:197], 0, s[34:35]
	s_add_i32 s15, s96, s94
	s_mov_b32 s18, m0
	s_mov_b32 m0, s15
	s_nop 0
	global_load_lds_dwordx4 v[82:83], off
	s_mov_b32 m0, s18
	v_max_f32_e32 v82, v67, v67
	v_max_f32_e32 v83, v66, v66
	v_max_f32_e32 v82, v83, v82
	s_nop 1
	v_max3_f32 v83, v68, v69, v51
	v_max3_f32 v82, v82, v50, v52
	v_max3_f32 v82, v82, v53, v70
	v_max3_f32 v83, v83, v72, v73
	v_max3_f32 v82, v82, v71, v54
	v_max3_f32 v83, v83, v56, v57
	v_max3_f32 v82, v82, v55, v74
	v_max3_f32 v83, v83, v76, v77
	v_max3_f32 v82, v82, v75, v58
	v_max3_f32 v83, v83, v60, v61
	v_max3_f32 v82, v82, v59, v78
	v_max3_f32 v83, v83, v80, v81
	v_max3_f32 v82, v82, v79, v62
	v_max3_f32 v83, v83, v64, v65
	v_max3_f32 v82, v82, v63, v83
	v_mov_b32_e32 v83, v82
	s_nop 1
	v_permlane32_swap_b32_e32 v82, v83
	v_max_f32_e32 v83, v83, v83
	v_max_f32_e32 v82, v82, v82
	v_max_f32_e32 v82, v82, v83
	v_lshl_add_u64 v[188:189], v[188:189], 0, s[28:29]
	s_add_i32 s15, s65, s93
	s_mov_b32 s18, m0
	s_mov_b32 m0, s15
	s_nop 0
	global_load_lds_dwordx4 v[188:189], off
	s_mov_b32 m0, s18
	v_cmp_lt_f32_e32 vcc, s82, v82
	s_cmp_lg_u64 vcc, 0
	v_add_f32_e32 v182, v213, v84
	s_cselect_b64 s[60:61], -1, 0
	s_cbranch_vccnz .LBB0_2488

.LBB0_2494:
	ds_read_b64_tr_b16 v[166:167], v209 offset:40960
	ds_read_b64_tr_b16 v[168:169], v209 offset:41472
	v_mfma_f32_32x32x16_bf16 v[114:129], v[58:61], v[142:145], v[34:49]
	v_add_f32_e32 v50, v98, v99
	v_add_f32_e32 v50, v100, v50
	v_add_f32_e32 v50, v101, v50
	v_add_f32_e32 v50, v102, v50
	v_add_f32_e32 v50, v103, v50
	v_cvt_pk_bf16_f32 v158, v98, v99
	v_cvt_pk_bf16_f32 v159, v100, v101
	ds_read_b64_tr_b16 v[162:163], v209 offset:45056
	ds_read_b64_tr_b16 v[164:165], v209 offset:45568
	v_add_f32_e32 v50, v104, v50
	v_add_f32_e32 v50, v105, v50
	v_add_f32_e32 v50, v106, v50
	v_add_f32_e32 v66, v107, v50
	v_mfma_f32_32x32x16_bf16 v[50:65], v[182:185], v[142:145], v[34:49]
	v_cvt_pk_bf16_f32 v160, v102, v103
	v_cvt_pk_bf16_f32 v161, v104, v105
	ds_read_b64_tr_b16 v[102:103], v209 offset:41984
	ds_read_b64_tr_b16 v[104:105], v209 offset:42496
	v_mfma_f32_32x32x16_bf16 v[114:129], v[186:189], v[138:141], v[114:129]
	v_add_f32_e32 v66, v108, v66
	v_add_f32_e32 v66, v109, v66
	v_add_f32_e32 v66, v110, v66
	v_add_f32_e32 v66, v111, v66
	v_cvt_pk_bf16_f32 v154, v106, v107
	v_cvt_pk_bf16_f32 v155, v108, v109
	ds_read_b64_tr_b16 v[98:99], v209 offset:46080
	ds_read_b64_tr_b16 v[100:101], v209 offset:46592
	v_mfma_f32_32x32x16_bf16 v[50:65], v[78:81], v[138:141], v[50:65]
	v_add_f32_e32 v66, v112, v66
	v_add_f32_e32 v66, v113, v66
	v_add_f32_e32 v66, v82, v66
	v_add_f32_e32 v66, v83, v66
	v_cvt_pk_bf16_f32 v156, v110, v111
	v_cvt_pk_bf16_f32 v157, v112, v113
	ds_read_b64_tr_b16 v[78:79], v209 offset:43008
	ds_read_b64_tr_b16 v[80:81], v209 offset:43520
	v_mfma_f32_32x32x16_bf16 v[114:129], v[74:77], v[134:137], v[114:129]
	v_add_f32_e32 v66, v84, v66
	v_add_f32_e32 v66, v85, v66
	v_add_f32_e32 v66, v86, v66
	v_add_f32_e32 v66, v87, v66
	v_cvt_pk_bf16_f32 v150, v82, v83
	v_cvt_pk_bf16_f32 v151, v84, v85
	ds_read_b64_tr_b16 v[74:75], v209 offset:47104
	ds_read_b64_tr_b16 v[76:77], v209 offset:47616
	v_mfma_f32_32x32x16_bf16 v[50:65], v[174:177], v[134:137], v[50:65]
	v_add_f32_e32 v66, v88, v66
	v_add_f32_e32 v66, v89, v66
	v_add_f32_e32 v66, v90, v66
	v_add_f32_e32 v66, v91, v66
	v_cvt_pk_bf16_f32 v152, v86, v87
	v_cvt_pk_bf16_f32 v153, v88, v89
	ds_read_b64_tr_b16 v[70:71], v209 offset:44032
	ds_read_b64_tr_b16 v[72:73], v209 offset:44544
	v_mfma_f32_32x32x16_bf16 v[114:129], v[178:181], v[130:133], v[114:129]
	v_add_f32_e32 v66, v92, v66
	v_add_f32_e32 v66, v93, v66
	v_add_f32_e32 v66, v94, v66
	v_add_f32_e32 v82, v95, v66
	v_cvt_pk_bf16_f32 v146, v90, v91
	v_cvt_pk_bf16_f32 v147, v92, v93
	ds_read_b64_tr_b16 v[66:67], v209 offset:48128
	ds_read_b64_tr_b16 v[68:69], v209 offset:48640
	v_mfma_f32_32x32x16_bf16 v[50:65], v[170:173], v[130:133], v[50:65]
	v_add_f32_e32 v82, v96, v82
	v_add_f32_e32 v82, v97, v82
	v_add_f32_e32 v82, 0, v82
	v_cvt_pk_bf16_f32 v148, v94, v95
	v_cvt_pk_bf16_f32 v149, v96, v97
	s_cmp_lg_u32 0, -1
	s_mov_b64 s[18:19], 0xf8000
	s_cselect_b32 s15, 0, 0
	v_add_f32_e32 v182, v197, v82
	v_lshl_add_u64 v[82:83], v[194:195], 0, s[18:19]
	s_add_i32 s15, s15, s69
	s_add_i32 s15, s15, 0x8000
	s_mov_b32 s18, m0
	s_mov_b32 m0, s15
	s_nop 0
	global_load_lds_dwordx4 v[82:83], off
	s_mov_b32 m0, s18
	v_max_f32_e32 v82, v115, v115
	v_max_f32_e32 v83, v114, v114
	v_max_f32_e32 v82, v83, v82
	v_max3_f32 v83, v116, v117, v51
	v_max3_f32 v82, v82, v50, v52
	v_max3_f32 v82, v82, v53, v118
	v_max3_f32 v83, v83, v120, v121
	v_max3_f32 v82, v82, v119, v54
	v_max3_f32 v83, v83, v56, v57
	v_max3_f32 v82, v82, v55, v122
	v_max3_f32 v83, v83, v124, v125
	v_max3_f32 v82, v82, v123, v58
	v_max3_f32 v83, v83, v60, v61
	v_max3_f32 v82, v82, v59, v126
	v_max3_f32 v83, v83, v128, v129
	v_max3_f32 v82, v82, v127, v62
	v_max3_f32 v83, v83, v64, v65
	v_max3_f32 v82, v82, v63, v83
	v_mov_b32_e32 v83, v82
	s_nop 1
	v_permlane32_swap_b32_e32 v82, v83
	v_max_f32_e32 v83, v83, v83
	v_max_f32_e32 v82, v82, v82
	v_max_f32_e32 v82, v82, v83
	v_cmp_lt_f32_e32 vcc, s82, v82
	s_cmp_lg_u64 vcc, 0
	s_cselect_b64 s[60:61], -1, 0
	s_cbranch_vccnz .LBB0_2601

.LBB0_2497:
	ds_read_b64_tr_b16 v[162:163], v209 offset:24576
	ds_read_b64_tr_b16 v[164:165], v209 offset:25088
	v_mfma_f32_32x32x16_bf16 v[82:97], v[110:113], v[142:145], v[34:49]
	v_add_f32_e32 v66, v114, v115
	v_add_f32_e32 v66, v116, v66
	v_add_f32_e32 v66, v117, v66
	v_add_f32_e32 v66, v118, v66
	v_add_f32_e32 v66, v119, v66
	v_cvt_pk_bf16_f32 v158, v114, v115
	v_cvt_pk_bf16_f32 v159, v116, v117
	ds_read_b64_tr_b16 v[114:115], v209 offset:28672
	ds_read_b64_tr_b16 v[116:117], v209 offset:29184
	v_add_f32_e32 v66, v120, v66
	v_add_f32_e32 v66, v121, v66
	v_add_f32_e32 v66, v122, v66
	v_add_f32_e32 v146, v123, v66
	v_mfma_f32_32x32x16_bf16 v[66:81], v[106:109], v[142:145], v[34:49]
	v_cvt_pk_bf16_f32 v160, v118, v119
	v_cvt_pk_bf16_f32 v161, v120, v121
	ds_read_b64_tr_b16 v[110:111], v209 offset:25600
	ds_read_b64_tr_b16 v[112:113], v209 offset:26112
	v_mfma_f32_32x32x16_bf16 v[82:97], v[178:181], v[138:141], v[82:97]
	v_add_f32_e32 v106, v124, v146
	v_add_f32_e32 v106, v125, v106
	v_add_f32_e32 v106, v126, v106
	v_add_f32_e32 v118, v127, v106
	v_cvt_pk_bf16_f32 v154, v122, v123
	v_cvt_pk_bf16_f32 v155, v124, v125
	ds_read_b64_tr_b16 v[106:107], v209 offset:29696
	ds_read_b64_tr_b16 v[108:109], v209 offset:30208
	v_mfma_f32_32x32x16_bf16 v[66:81], v[102:105], v[138:141], v[66:81]
	v_add_f32_e32 v118, v128, v118
	v_add_f32_e32 v118, v129, v118
	v_add_f32_e32 v118, v50, v118
	v_add_f32_e32 v118, v51, v118
	v_cvt_pk_bf16_f32 v156, v126, v127
	v_cvt_pk_bf16_f32 v157, v128, v129
	ds_read_b64_tr_b16 v[102:103], v209 offset:26624
	ds_read_b64_tr_b16 v[104:105], v209 offset:27136
	v_mfma_f32_32x32x16_bf16 v[82:97], v[98:101], v[134:137], v[82:97]
	v_add_f32_e32 v118, v52, v118
	v_add_f32_e32 v118, v53, v118
	v_add_f32_e32 v118, v54, v118
	v_add_f32_e32 v118, v55, v118
	v_cvt_pk_bf16_f32 v150, v50, v51
	v_cvt_pk_bf16_f32 v151, v52, v53
	ds_read_b64_tr_b16 v[98:99], v209 offset:30720
	ds_read_b64_tr_b16 v[100:101], v209 offset:31232
	v_mfma_f32_32x32x16_bf16 v[66:81], v[170:173], v[134:137], v[66:81]
	v_add_f32_e32 v50, v56, v118
	v_add_f32_e32 v50, v57, v50
	v_add_f32_e32 v50, v58, v50
	v_add_f32_e32 v50, v59, v50
	v_cvt_pk_bf16_f32 v152, v54, v55
	v_cvt_pk_bf16_f32 v153, v56, v57
	ds_read_b64_tr_b16 v[54:55], v209 offset:27648
	ds_read_b64_tr_b16 v[56:57], v209 offset:28160
	v_mfma_f32_32x32x16_bf16 v[82:97], v[174:177], v[130:133], v[82:97]
	v_add_f32_e32 v50, v60, v50
	v_add_f32_e32 v50, v61, v50
	v_add_f32_e32 v50, v62, v50
	v_add_f32_e32 v118, v63, v50
	v_cvt_pk_bf16_f32 v146, v58, v59
	v_cvt_pk_bf16_f32 v147, v60, v61
	ds_read_b64_tr_b16 v[50:51], v209 offset:31744
	ds_read_b64_tr_b16 v[52:53], v209 offset:32256
	v_mfma_f32_32x32x16_bf16 v[66:81], v[166:169], v[130:133], v[66:81]
	v_add_f32_e32 v58, v64, v118
	v_add_f32_e32 v58, v65, v58
	v_add_f32_e32 v58, 0, v58
	v_cvt_pk_bf16_f32 v148, v62, v63
	v_cvt_pk_bf16_f32 v149, v64, v65
	s_cmp_lg_u32 0, -1
	s_cselect_b32 s15, 0, 0
	v_add_f32_e32 v118, v182, v58
	v_lshl_add_u64 v[58:59], v[194:195], 0, s[36:37]
	s_add_i32 s15, s15, s69
	s_add_i32 s15, s15, 0xa000
	s_mov_b32 s18, m0
	s_mov_b32 m0, s15
	s_nop 0
	global_load_lds_dwordx4 v[58:59], off
	s_mov_b32 m0, s18
	v_max_f32_e32 v58, v83, v83
	v_max_f32_e32 v59, v82, v82
	v_max_f32_e32 v58, v59, v58
	v_max3_f32 v59, v84, v85, v67
	v_max3_f32 v58, v58, v66, v68
	v_max3_f32 v58, v58, v69, v86
	v_max3_f32 v59, v59, v88, v89
	v_max3_f32 v58, v58, v87, v70
	v_max3_f32 v59, v59, v72, v73
	v_max3_f32 v58, v58, v71, v90
	v_max3_f32 v59, v59, v92, v93
	v_max3_f32 v58, v58, v91, v74
	v_max3_f32 v59, v59, v76, v77
	v_max3_f32 v58, v58, v75, v94
	v_max3_f32 v59, v59, v96, v97
	v_max3_f32 v58, v58, v95, v78
	v_max3_f32 v59, v59, v80, v81
	v_max3_f32 v58, v58, v79, v59
	v_mov_b32_e32 v59, v58
	s_nop 1
	v_permlane32_swap_b32_e32 v58, v59
	v_max_f32_e32 v59, v59, v59
	v_max_f32_e32 v58, v58, v58
	v_max_f32_e32 v58, v58, v59
	v_cmp_lt_f32_e32 vcc, s82, v58
	s_cmp_lg_u64 vcc, 0
	s_cselect_b64 s[60:61], -1, 0
	s_cbranch_vccnz .LBB0_2604

; __device__ __forceinline__ void kmask(f32x16&p0,f32x16&p1,int rem,int hi){
;   const float NEG=-INFINITY;
;   #pragma unroll
;   for(int r=0;r<16;++r){int kv=4*hi+(r&3)+8*(r>>2); if(kv>=rem)p0[r]=NEG; if(kv+32>=rem)p1[r]=NEG;}
; }
.LBB0_2500:
	ds_read_b64_tr_b16 v[62:63], v209 offset:32768
	ds_read_b64_tr_b16 v[64:65], v209 offset:33280
	v_mfma_f32_32x32x16_bf16 v[34:49], v[114:117], v[142:145], v[34:49]
	v_add_f32_e32 v50, v82, v83
	v_add_f32_e32 v50, v84, v50
	v_add_f32_e32 v50, v85, v50
	v_add_f32_e32 v50, v86, v50
	v_add_f32_e32 v50, v87, v50
	v_cvt_pk_bf16_f32 v158, v82, v83
	v_cvt_pk_bf16_f32 v159, v84, v85
	ds_read_b64_tr_b16 v[102:103], v209 offset:36864
	ds_read_b64_tr_b16 v[104:105], v209 offset:37376
	v_add_f32_e32 v50, v88, v50
	v_add_f32_e32 v50, v89, v50
	v_add_f32_e32 v50, v90, v50
	v_add_f32_e32 v50, v91, v50
	v_cvt_pk_bf16_f32 v160, v86, v87
	v_cvt_pk_bf16_f32 v161, v88, v89
	ds_read_b64_tr_b16 v[98:99], v209 offset:33792
	ds_read_b64_tr_b16 v[100:101], v209 offset:34304
	v_mfma_f32_32x32x16_bf16 v[34:49], v[110:113], v[138:141], v[34:49]
	v_add_f32_e32 v50, v92, v50
	v_add_f32_e32 v50, v93, v50
	v_add_f32_e32 v50, v94, v50
	v_add_f32_e32 v50, v95, v50
	v_cvt_pk_bf16_f32 v154, v90, v91
	v_cvt_pk_bf16_f32 v155, v92, v93
	ds_read_b64_tr_b16 v[90:91], v209 offset:37888
	ds_read_b64_tr_b16 v[92:93], v209 offset:38400
	v_add_f32_e32 v50, v96, v50
	v_add_f32_e32 v50, v97, v50
	v_add_f32_e32 v50, v66, v50
	v_add_f32_e32 v50, v67, v50
	v_cvt_pk_bf16_f32 v156, v94, v95
	v_cvt_pk_bf16_f32 v157, v96, v97
	ds_read_b64_tr_b16 v[86:87], v209 offset:34816
	ds_read_b64_tr_b16 v[88:89], v209 offset:35328
	v_mfma_f32_32x32x16_bf16 v[34:49], v[106:109], v[134:137], v[34:49]
	v_add_f32_e32 v50, v68, v50
	v_add_f32_e32 v50, v69, v50
	v_add_f32_e32 v50, v70, v50
	v_add_f32_e32 v50, v71, v50
	v_cvt_pk_bf16_f32 v150, v66, v67
	v_cvt_pk_bf16_f32 v151, v68, v69
	ds_read_b64_tr_b16 v[82:83], v209 offset:38912
	ds_read_b64_tr_b16 v[84:85], v209 offset:39424
	v_add_f32_e32 v50, v72, v50
	v_add_f32_e32 v50, v73, v50
	v_add_f32_e32 v50, v74, v50
	v_add_f32_e32 v50, v75, v50
	v_cvt_pk_bf16_f32 v152, v70, v71
	v_cvt_pk_bf16_f32 v153, v72, v73
	ds_read_b64_tr_b16 v[70:71], v209 offset:35840
	ds_read_b64_tr_b16 v[72:73], v209 offset:36352
	v_mfma_f32_32x32x16_bf16 v[34:49], v[58:61], v[130:133], v[34:49]
	v_add_f32_e32 v50, v76, v50
	v_add_f32_e32 v50, v77, v50
	v_add_f32_e32 v50, v78, v50
	v_add_f32_e32 v50, v79, v50
	v_cvt_pk_bf16_f32 v146, v74, v75
	v_cvt_pk_bf16_f32 v147, v76, v77
	ds_read_b64_tr_b16 v[66:67], v209 offset:39936
	ds_read_b64_tr_b16 v[68:69], v209 offset:40448
	s_nop 3
	v_add_f32_e32 v42, v80, v50
	v_add_f32_e32 v42, v81, v42
	v_add_f32_e32 v42, 0, v42
	v_cvt_pk_bf16_f32 v148, v78, v79
	v_cvt_pk_bf16_f32 v149, v80, v81
	v_max_f32_e32 v44, v37, v37
	v_max_f32_e32 v45, v36, v36
	v_add_f32_e32 v74, v118, v42
	v_mov_b32_e32 v42, 0xff800000
	v_max_f32_e32 v44, v45, v44
	v_max3_f32 v43, v34, v35, v42
	v_max3_f32 v44, v44, v42, v40
	v_max3_f32 v43, v43, v38, v39
	v_max3_f32 v44, v44, v41, v42
	v_max3_f32 v43, v43, v42, v44
	v_mov_b32_e32 v44, v43
	s_nop 1
	v_permlane32_swap_b32_e32 v43, v44
	v_max_f32_e32 v44, v44, v44
	v_max_f32_e32 v43, v43, v43
	v_max_f32_e32 v43, v43, v44
	v_cmp_lt_f32_e32 vcc, s82, v43
	s_cmp_lg_u64 vcc, 0
	s_cselect_b64 s[60:61], -1, 0
	s_cbranch_vccnz .LBB0_2607

.LBB0_2518:
	v_add_u32_e32 v183, s18, v208
	ds_read_b64_tr_b16 v[178:179], v183 offset:24576
	ds_read_b64_tr_b16 v[180:181], v183 offset:25088
	v_mfma_f32_32x32x16_bf16 v[98:113], v[82:85], v[142:145], v[34:49]
	v_add_f32_e32 v86, v66, v67
	v_add_f32_e32 v86, v68, v86
	v_add_f32_e32 v86, v69, v86
	v_add_f32_e32 v86, v70, v86
	v_add_f32_e32 v86, v71, v86
	v_cvt_pk_bf16_f32 v158, v66, v67
	v_cvt_pk_bf16_f32 v159, v68, v69
	ds_read_b64_tr_b16 v[174:175], v183 offset:28672
	ds_read_b64_tr_b16 v[176:177], v183 offset:29184
	v_add_f32_e32 v66, v72, v86
	v_mfma_f32_32x32x16_bf16 v[82:97], v[170:173], v[142:145], v[34:49]
	v_add_f32_e32 v66, v73, v66
	v_add_f32_e32 v66, v74, v66
	v_add_f32_e32 v66, v75, v66
	v_cvt_pk_bf16_f32 v160, v70, v71
	v_cvt_pk_bf16_f32 v161, v72, v73
	ds_read_b64_tr_b16 v[170:171], v183 offset:25600
	ds_read_b64_tr_b16 v[172:173], v183 offset:26112
	v_mfma_f32_32x32x16_bf16 v[98:113], v[166:169], v[138:141], v[98:113]
	v_add_f32_e32 v66, v76, v66
	v_add_f32_e32 v66, v77, v66
	v_add_f32_e32 v66, v78, v66
	v_add_f32_e32 v66, v79, v66
	v_cvt_pk_bf16_f32 v154, v74, v75
	v_cvt_pk_bf16_f32 v155, v76, v77
	ds_read_b64_tr_b16 v[74:75], v183 offset:29696
	ds_read_b64_tr_b16 v[76:77], v183 offset:30208
	v_mfma_f32_32x32x16_bf16 v[82:97], v[162:165], v[138:141], v[82:97]
	v_add_f32_e32 v66, v80, v66
	v_add_f32_e32 v66, v81, v66
	v_add_f32_e32 v66, v50, v66
	v_add_f32_e32 v66, v51, v66
	v_cvt_pk_bf16_f32 v156, v78, v79
	v_cvt_pk_bf16_f32 v157, v80, v81
	ds_read_b64_tr_b16 v[70:71], v183 offset:26624
	ds_read_b64_tr_b16 v[72:73], v183 offset:27136
	v_mfma_f32_32x32x16_bf16 v[98:113], v[126:129], v[134:137], v[98:113]
	v_add_f32_e32 v66, v52, v66
	v_add_f32_e32 v66, v53, v66
	v_add_f32_e32 v66, v54, v66
	v_add_f32_e32 v78, v55, v66
	v_cvt_pk_bf16_f32 v150, v50, v51
	v_cvt_pk_bf16_f32 v151, v52, v53
	ds_read_b64_tr_b16 v[66:67], v183 offset:30720
	ds_read_b64_tr_b16 v[68:69], v183 offset:31232
	v_mfma_f32_32x32x16_bf16 v[82:97], v[122:125], v[134:137], v[82:97]
	v_add_f32_e32 v50, v56, v78
	v_add_f32_e32 v50, v57, v50
	v_add_f32_e32 v50, v58, v50
	v_add_f32_e32 v50, v59, v50
	v_cvt_pk_bf16_f32 v152, v54, v55
	v_cvt_pk_bf16_f32 v153, v56, v57
	ds_read_b64_tr_b16 v[54:55], v183 offset:27648
	ds_read_b64_tr_b16 v[56:57], v183 offset:28160
	v_mfma_f32_32x32x16_bf16 v[98:113], v[118:121], v[130:133], v[98:113]
	v_add_f32_e32 v50, v60, v50
	v_add_f32_e32 v50, v61, v50
	v_add_f32_e32 v50, v62, v50
	v_add_f32_e32 v78, v63, v50
	v_cvt_pk_bf16_f32 v146, v58, v59
	v_cvt_pk_bf16_f32 v147, v60, v61
	ds_read_b64_tr_b16 v[50:51], v183 offset:31744
	ds_read_b64_tr_b16 v[52:53], v183 offset:32256
	v_mfma_f32_32x32x16_bf16 v[82:97], v[114:117], v[130:133], v[82:97]
	v_add_f32_e32 v58, v64, v78
	v_add_f32_e32 v58, v65, v58
	v_add_f32_e32 v60, 0, v58
	v_cvt_pk_bf16_f32 v148, v62, v63
	v_cvt_pk_bf16_f32 v149, v64, v65
	v_lshl_add_u64 v[58:59], v[196:197], 0, s[30:31]
	s_add_i32 s15, s64, s93
	s_mov_b32 s18, m0
	s_mov_b32 m0, s15
	s_nop 0
	global_load_lds_dwordx4 v[58:59], off
	s_mov_b32 m0, s18
	v_lshl_add_u64 v[58:59], v[188:189], 0, s[26:27]
	s_add_i32 s15, s95, s69
	s_mov_b32 s18, m0
	s_mov_b32 m0, s15
	s_nop 0
	global_load_lds_dwordx4 v[58:59], off
	s_mov_b32 m0, s18
	v_max_f32_e32 v58, v99, v99
	v_max_f32_e32 v59, v98, v98
	v_max_f32_e32 v58, v59, v58
	v_max3_f32 v59, v100, v101, v83
	v_max3_f32 v58, v58, v82, v84
	v_max3_f32 v58, v58, v85, v102
	v_max3_f32 v59, v59, v104, v105
	v_max3_f32 v58, v58, v103, v86
	v_max3_f32 v59, v59, v88, v89
	v_max3_f32 v58, v58, v87, v106
	v_max3_f32 v59, v59, v108, v109
	v_max3_f32 v58, v58, v107, v90
	v_max3_f32 v59, v59, v92, v93
	v_max3_f32 v58, v58, v91, v110
	v_max3_f32 v59, v59, v112, v113
	v_max3_f32 v58, v58, v111, v94
	v_max3_f32 v59, v59, v96, v97
	v_max3_f32 v58, v58, v95, v59
	v_mov_b32_e32 v59, v58
	s_nop 1
	v_permlane32_swap_b32_e32 v58, v59
	v_max_f32_e32 v59, v59, v59
	v_max_f32_e32 v58, v58, v58
	v_max_f32_e32 v58, v58, v59
	v_cmp_lt_f32_e32 vcc, s82, v58
	s_cmp_lg_u64 vcc, 0
	v_add_f32_e32 v192, v182, v60
	s_cselect_b64 s[60:61], -1, 0
	s_cbranch_vccnz .LBB0_2526

.LBB0_2521:
	s_add_i32 s15, s95, 0x2000
	s_cmpk_lg_i32 s95, 0x4000
	s_cselect_b32 s65, s15, 0
	v_add_u32_e32 v203, s64, v208
	ds_read_b64_tr_b16 v[126:127], v203 offset:24576
	ds_read_b64_tr_b16 v[128:129], v203 offset:25088
	v_mfma_f32_32x32x16_bf16 v[66:81], v[58:61], v[142:145], v[34:49]
	v_add_f32_e32 v50, v98, v99
	v_add_f32_e32 v50, v100, v50
	v_add_f32_e32 v50, v101, v50
	v_add_f32_e32 v50, v102, v50
	v_add_f32_e32 v50, v103, v50
	v_cvt_pk_bf16_f32 v158, v98, v99
	v_cvt_pk_bf16_f32 v159, v100, v101
	ds_read_b64_tr_b16 v[122:123], v203 offset:28672
	ds_read_b64_tr_b16 v[124:125], v203 offset:29184
	v_add_f32_e32 v50, v104, v50
	v_add_f32_e32 v50, v105, v50
	v_add_f32_e32 v50, v106, v50
	v_add_f32_e32 v98, v107, v50
	v_mfma_f32_32x32x16_bf16 v[50:65], v[114:117], v[142:145], v[34:49]
	v_cvt_pk_bf16_f32 v160, v102, v103
	v_cvt_pk_bf16_f32 v161, v104, v105
	ds_read_b64_tr_b16 v[118:119], v203 offset:25600
	ds_read_b64_tr_b16 v[120:121], v203 offset:26112
	v_mfma_f32_32x32x16_bf16 v[66:81], v[182:185], v[138:141], v[66:81]
	v_add_f32_e32 v98, v108, v98
	v_add_f32_e32 v98, v109, v98
	v_add_f32_e32 v98, v110, v98
	v_add_f32_e32 v98, v111, v98
	v_cvt_pk_bf16_f32 v154, v106, v107
	v_cvt_pk_bf16_f32 v155, v108, v109
	ds_read_b64_tr_b16 v[114:115], v203 offset:29696
	ds_read_b64_tr_b16 v[116:117], v203 offset:30208
	v_mfma_f32_32x32x16_bf16 v[50:65], v[174:177], v[138:141], v[50:65]
	v_add_f32_e32 v98, v112, v98
	v_add_f32_e32 v98, v113, v98
	v_add_f32_e32 v98, v82, v98
	v_add_f32_e32 v98, v83, v98
	v_cvt_pk_bf16_f32 v156, v110, v111
	v_cvt_pk_bf16_f32 v157, v112, v113
	ds_read_b64_tr_b16 v[106:107], v203 offset:26624
	ds_read_b64_tr_b16 v[108:109], v203 offset:27136
	v_mfma_f32_32x32x16_bf16 v[66:81], v[178:181], v[134:137], v[66:81]
	v_add_f32_e32 v98, v84, v98
	v_add_f32_e32 v98, v85, v98
	v_add_f32_e32 v98, v86, v98
	v_add_f32_e32 v98, v87, v98
	v_cvt_pk_bf16_f32 v150, v82, v83
	v_cvt_pk_bf16_f32 v151, v84, v85
	ds_read_b64_tr_b16 v[102:103], v203 offset:30720
	ds_read_b64_tr_b16 v[104:105], v203 offset:31232
	v_mfma_f32_32x32x16_bf16 v[50:65], v[166:169], v[134:137], v[50:65]
	v_add_f32_e32 v82, v88, v98
	v_add_f32_e32 v82, v89, v82
	v_add_f32_e32 v82, v90, v82
	v_add_f32_e32 v82, v91, v82
	v_cvt_pk_bf16_f32 v152, v86, v87
	v_cvt_pk_bf16_f32 v153, v88, v89
	ds_read_b64_tr_b16 v[98:99], v203 offset:27648
	ds_read_b64_tr_b16 v[100:101], v203 offset:28160
	v_mfma_f32_32x32x16_bf16 v[66:81], v[170:173], v[130:133], v[66:81]
	v_add_f32_e32 v82, v92, v82
	v_add_f32_e32 v82, v93, v82
	v_add_f32_e32 v82, v94, v82
	v_add_f32_e32 v82, v95, v82
	v_cvt_pk_bf16_f32 v146, v90, v91
	v_cvt_pk_bf16_f32 v147, v92, v93
	ds_read_b64_tr_b16 v[86:87], v203 offset:31744
	ds_read_b64_tr_b16 v[88:89], v203 offset:32256
	v_mfma_f32_32x32x16_bf16 v[50:65], v[162:165], v[130:133], v[50:65]
	v_add_f32_e32 v82, v96, v82
	v_add_f32_e32 v82, v97, v82
	v_add_f32_e32 v84, 0, v82
	v_cvt_pk_bf16_f32 v148, v94, v95
	v_cvt_pk_bf16_f32 v149, v96, v97
	v_lshl_add_u64 v[82:83], v[196:197], 0, s[34:35]
	s_add_i32 s15, s95, s93
	s_mov_b32 s18, m0
	s_mov_b32 m0, s15
	s_nop 0
	global_load_lds_dwordx4 v[82:83], off
	s_mov_b32 m0, s18
	v_max_f32_e32 v82, v67, v67
	v_max_f32_e32 v83, v66, v66
	v_max_f32_e32 v82, v83, v82
	s_nop 1
	v_max3_f32 v83, v68, v69, v51
	v_max3_f32 v82, v82, v50, v52
	v_max3_f32 v82, v82, v53, v70
	v_max3_f32 v83, v83, v72, v73
	v_max3_f32 v82, v82, v71, v54
	v_max3_f32 v83, v83, v56, v57
	v_max3_f32 v82, v82, v55, v74
	v_max3_f32 v83, v83, v76, v77
	v_max3_f32 v82, v82, v75, v58
	v_max3_f32 v83, v83, v60, v61
	v_max3_f32 v82, v82, v59, v78
	v_max3_f32 v83, v83, v80, v81
	v_max3_f32 v82, v82, v79, v62
	v_max3_f32 v83, v83, v64, v65
	v_max3_f32 v82, v82, v63, v83
	v_mov_b32_e32 v83, v82
	s_nop 1
	v_permlane32_swap_b32_e32 v82, v83
	v_max_f32_e32 v83, v83, v83
	v_max_f32_e32 v82, v82, v82
	v_max_f32_e32 v82, v82, v83
	v_lshl_add_u64 v[188:189], v[188:189], 0, s[28:29]
	s_add_i32 s15, s65, s69
	s_mov_b32 s18, m0
	s_mov_b32 m0, s15
	s_nop 0
	global_load_lds_dwordx4 v[188:189], off
	s_mov_b32 m0, s18
	v_cmp_lt_f32_e32 vcc, s82, v82
	s_cmp_lg_u64 vcc, 0
	v_add_f32_e32 v182, v192, v84
	s_cselect_b64 s[60:61], -1, 0
	s_cbranch_vccnz .LBB0_2529

.LBB0_2535:
	ds_read_b64_tr_b16 v[166:167], v208 offset:32768
	ds_read_b64_tr_b16 v[168:169], v208 offset:33280
	v_mfma_f32_32x32x16_bf16 v[114:129], v[58:61], v[142:145], v[34:49]
	v_add_f32_e32 v50, v98, v99
	v_add_f32_e32 v50, v100, v50
	v_add_f32_e32 v50, v101, v50
	v_add_f32_e32 v50, v102, v50
	v_add_f32_e32 v50, v103, v50
	v_cvt_pk_bf16_f32 v158, v98, v99
	v_cvt_pk_bf16_f32 v159, v100, v101
	ds_read_b64_tr_b16 v[162:163], v208 offset:36864
	ds_read_b64_tr_b16 v[164:165], v208 offset:37376
	v_add_f32_e32 v50, v104, v50
	v_add_f32_e32 v50, v105, v50
	v_add_f32_e32 v50, v106, v50
	v_add_f32_e32 v66, v107, v50
	v_mfma_f32_32x32x16_bf16 v[50:65], v[182:185], v[142:145], v[34:49]
	v_cvt_pk_bf16_f32 v160, v102, v103
	v_cvt_pk_bf16_f32 v161, v104, v105
	ds_read_b64_tr_b16 v[102:103], v208 offset:33792
	ds_read_b64_tr_b16 v[104:105], v208 offset:34304
	v_mfma_f32_32x32x16_bf16 v[114:129], v[186:189], v[138:141], v[114:129]
	v_add_f32_e32 v66, v108, v66
	v_add_f32_e32 v66, v109, v66
	v_add_f32_e32 v66, v110, v66
	v_add_f32_e32 v66, v111, v66
	v_cvt_pk_bf16_f32 v154, v106, v107
	v_cvt_pk_bf16_f32 v155, v108, v109
	ds_read_b64_tr_b16 v[98:99], v208 offset:37888
	ds_read_b64_tr_b16 v[100:101], v208 offset:38400
	v_mfma_f32_32x32x16_bf16 v[50:65], v[78:81], v[138:141], v[50:65]
	v_add_f32_e32 v66, v112, v66
	v_add_f32_e32 v66, v113, v66
	v_add_f32_e32 v66, v82, v66
	v_add_f32_e32 v66, v83, v66
	v_cvt_pk_bf16_f32 v156, v110, v111
	v_cvt_pk_bf16_f32 v157, v112, v113
	ds_read_b64_tr_b16 v[78:79], v208 offset:34816
	ds_read_b64_tr_b16 v[80:81], v208 offset:35328
	v_mfma_f32_32x32x16_bf16 v[114:129], v[74:77], v[134:137], v[114:129]
	v_add_f32_e32 v66, v84, v66
	v_add_f32_e32 v66, v85, v66
	v_add_f32_e32 v66, v86, v66
	v_add_f32_e32 v66, v87, v66
	v_cvt_pk_bf16_f32 v150, v82, v83
	v_cvt_pk_bf16_f32 v151, v84, v85
	ds_read_b64_tr_b16 v[74:75], v208 offset:38912
	ds_read_b64_tr_b16 v[76:77], v208 offset:39424
	v_mfma_f32_32x32x16_bf16 v[50:65], v[174:177], v[134:137], v[50:65]
	v_add_f32_e32 v66, v88, v66
	v_add_f32_e32 v66, v89, v66
	v_add_f32_e32 v66, v90, v66
	v_add_f32_e32 v66, v91, v66
	v_cvt_pk_bf16_f32 v152, v86, v87
	v_cvt_pk_bf16_f32 v153, v88, v89
	ds_read_b64_tr_b16 v[70:71], v208 offset:35840
	ds_read_b64_tr_b16 v[72:73], v208 offset:36352
	v_mfma_f32_32x32x16_bf16 v[114:129], v[178:181], v[130:133], v[114:129]
	v_add_f32_e32 v66, v92, v66
	v_add_f32_e32 v66, v93, v66
	v_add_f32_e32 v66, v94, v66
	v_add_f32_e32 v82, v95, v66
	v_cvt_pk_bf16_f32 v146, v90, v91
	v_cvt_pk_bf16_f32 v147, v92, v93
	ds_read_b64_tr_b16 v[66:67], v208 offset:39936
	ds_read_b64_tr_b16 v[68:69], v208 offset:40448
	v_mfma_f32_32x32x16_bf16 v[50:65], v[170:173], v[130:133], v[50:65]
	v_add_f32_e32 v82, v96, v82
	v_add_f32_e32 v82, v97, v82
	v_add_f32_e32 v82, 0, v82
	v_cvt_pk_bf16_f32 v148, v94, v95
	v_cvt_pk_bf16_f32 v149, v96, v97
	s_nop 0
	v_add_f32_e32 v182, v196, v82
	v_lshl_add_u64 v[82:83], v[194:195], 0, s[42:43]
	s_mov_b32 s15, m0
	s_mov_b32 m0, s69
	s_nop 0
	global_load_lds_dwordx4 v[82:83], off
	s_mov_b32 m0, s15
	v_max_f32_e32 v82, v115, v115
	v_max_f32_e32 v83, v114, v114
	v_max_f32_e32 v82, v83, v82
	s_nop 0
	v_max3_f32 v83, v116, v117, v51
	v_max3_f32 v82, v82, v50, v52
	v_max3_f32 v82, v82, v53, v118
	v_max3_f32 v83, v83, v120, v121
	v_max3_f32 v82, v82, v119, v54
	v_max3_f32 v83, v83, v56, v57
	v_max3_f32 v82, v82, v55, v122
	v_max3_f32 v83, v83, v124, v125
	v_max3_f32 v82, v82, v123, v58
	v_max3_f32 v83, v83, v60, v61
	v_max3_f32 v82, v82, v59, v126
	v_max3_f32 v83, v83, v128, v129
	v_max3_f32 v82, v82, v127, v62
	v_max3_f32 v83, v83, v64, v65
	v_max3_f32 v82, v82, v63, v83
	v_mov_b32_e32 v83, v82
	s_nop 1
	v_permlane32_swap_b32_e32 v82, v83
	v_max_f32_e32 v83, v83, v83
	v_max_f32_e32 v82, v82, v82
	v_max_f32_e32 v82, v82, v83
	v_cmp_lt_f32_e32 vcc, s82, v82
	s_cmp_lg_u64 vcc, 0
	s_cselect_b64 s[60:61], -1, 0
	s_cbranch_vccnz .LBB0_2613

.LBB0_2538:
	ds_read_b64_tr_b16 v[162:163], v208 offset:40960
	ds_read_b64_tr_b16 v[164:165], v208 offset:41472
	v_mfma_f32_32x32x16_bf16 v[82:97], v[110:113], v[142:145], v[34:49]
	v_add_f32_e32 v66, v114, v115
	v_add_f32_e32 v66, v116, v66
	v_add_f32_e32 v66, v117, v66
	v_add_f32_e32 v66, v118, v66
	v_add_f32_e32 v66, v119, v66
	v_cvt_pk_bf16_f32 v158, v114, v115
	v_cvt_pk_bf16_f32 v159, v116, v117
	ds_read_b64_tr_b16 v[114:115], v208 offset:45056
	ds_read_b64_tr_b16 v[116:117], v208 offset:45568
	v_add_f32_e32 v66, v120, v66
	v_add_f32_e32 v66, v121, v66
	v_add_f32_e32 v66, v122, v66
	v_add_f32_e32 v146, v123, v66
	v_mfma_f32_32x32x16_bf16 v[66:81], v[106:109], v[142:145], v[34:49]
	v_cvt_pk_bf16_f32 v160, v118, v119
	v_cvt_pk_bf16_f32 v161, v120, v121
	ds_read_b64_tr_b16 v[110:111], v208 offset:41984
	ds_read_b64_tr_b16 v[112:113], v208 offset:42496
	v_mfma_f32_32x32x16_bf16 v[82:97], v[178:181], v[138:141], v[82:97]
	v_add_f32_e32 v106, v124, v146
	v_add_f32_e32 v106, v125, v106
	v_add_f32_e32 v106, v126, v106
	v_add_f32_e32 v118, v127, v106
	v_cvt_pk_bf16_f32 v154, v122, v123
	v_cvt_pk_bf16_f32 v155, v124, v125
	ds_read_b64_tr_b16 v[106:107], v208 offset:46080
	ds_read_b64_tr_b16 v[108:109], v208 offset:46592
	v_mfma_f32_32x32x16_bf16 v[66:81], v[102:105], v[138:141], v[66:81]
	v_add_f32_e32 v118, v128, v118
	v_add_f32_e32 v118, v129, v118
	v_add_f32_e32 v118, v50, v118
	v_add_f32_e32 v118, v51, v118
	v_cvt_pk_bf16_f32 v156, v126, v127
	v_cvt_pk_bf16_f32 v157, v128, v129
	ds_read_b64_tr_b16 v[102:103], v208 offset:43008
	ds_read_b64_tr_b16 v[104:105], v208 offset:43520
	v_mfma_f32_32x32x16_bf16 v[82:97], v[98:101], v[134:137], v[82:97]
	v_add_f32_e32 v118, v52, v118
	v_add_f32_e32 v118, v53, v118
	v_add_f32_e32 v118, v54, v118
	v_add_f32_e32 v118, v55, v118
	v_cvt_pk_bf16_f32 v150, v50, v51
	v_cvt_pk_bf16_f32 v151, v52, v53
	ds_read_b64_tr_b16 v[98:99], v208 offset:47104
	ds_read_b64_tr_b16 v[100:101], v208 offset:47616
	v_mfma_f32_32x32x16_bf16 v[66:81], v[170:173], v[134:137], v[66:81]
	v_add_f32_e32 v50, v56, v118
	v_add_f32_e32 v50, v57, v50
	v_add_f32_e32 v50, v58, v50
	v_add_f32_e32 v50, v59, v50
	v_cvt_pk_bf16_f32 v152, v54, v55
	v_cvt_pk_bf16_f32 v153, v56, v57
	ds_read_b64_tr_b16 v[54:55], v208 offset:44032
	ds_read_b64_tr_b16 v[56:57], v208 offset:44544
	v_mfma_f32_32x32x16_bf16 v[82:97], v[174:177], v[130:133], v[82:97]
	v_add_f32_e32 v50, v60, v50
	v_add_f32_e32 v50, v61, v50
	v_add_f32_e32 v50, v62, v50
	v_add_f32_e32 v118, v63, v50
	v_cvt_pk_bf16_f32 v146, v58, v59
	v_cvt_pk_bf16_f32 v147, v60, v61
	ds_read_b64_tr_b16 v[50:51], v208 offset:48128
	ds_read_b64_tr_b16 v[52:53], v208 offset:48640
	v_mfma_f32_32x32x16_bf16 v[66:81], v[166:169], v[130:133], v[66:81]
	v_add_f32_e32 v58, v64, v118
	v_add_f32_e32 v58, v65, v58
	v_add_f32_e32 v58, 0, v58
	v_cvt_pk_bf16_f32 v148, v62, v63
	v_cvt_pk_bf16_f32 v149, v64, v65
	s_cmp_lg_u32 0, -1
	s_cselect_b32 s15, 0, 0
	v_add_f32_e32 v118, v182, v58
	v_lshl_add_u64 v[58:59], v[194:195], 0, s[38:39]
	s_add_i32 s15, s15, s68
	s_add_i32 s15, s15, 0x8000
	s_mov_b32 s18, m0
	s_mov_b32 m0, s15
	s_nop 0
	global_load_lds_dwordx4 v[58:59], off
	s_mov_b32 m0, s18
	v_max_f32_e32 v58, v83, v83
	v_max_f32_e32 v59, v82, v82
	v_max_f32_e32 v58, v59, v58
	v_max3_f32 v59, v84, v85, v67
	v_max3_f32 v58, v58, v66, v68
	v_max3_f32 v58, v58, v69, v86
	v_max3_f32 v59, v59, v88, v89
	v_max3_f32 v58, v58, v87, v70
	v_max3_f32 v59, v59, v72, v73
	v_max3_f32 v58, v58, v71, v90
	v_max3_f32 v59, v59, v92, v93
	v_max3_f32 v58, v58, v91, v74
	v_max3_f32 v59, v59, v76, v77
	v_max3_f32 v58, v58, v75, v94
	v_max3_f32 v59, v59, v96, v97
	v_max3_f32 v58, v58, v95, v78
	v_max3_f32 v59, v59, v80, v81
	v_max3_f32 v58, v58, v79, v59
	v_mov_b32_e32 v59, v58
	s_nop 1
	v_permlane32_swap_b32_e32 v58, v59
	v_max_f32_e32 v59, v59, v59
	v_max_f32_e32 v58, v58, v58
	v_max_f32_e32 v58, v58, v59
	v_cmp_lt_f32_e32 vcc, s82, v58
	s_cmp_lg_u64 vcc, 0
	s_cselect_b64 s[60:61], -1, 0
	s_cbranch_vccnz .LBB0_2616

; __device__ __forceinline__ void kmask(f32x16&p0,f32x16&p1,int rem,int hi){
;   const float NEG=-INFINITY;
;   #pragma unroll
;   for(int r=0;r<16;++r){int kv=4*hi+(r&3)+8*(r>>2); if(kv>=rem)p0[r]=NEG; if(kv+32>=rem)p1[r]=NEG;}
; }
.LBB0_2541:
	ds_read_b64_tr_b16 v[62:63], v208 offset:24576
	ds_read_b64_tr_b16 v[64:65], v208 offset:25088
	v_mfma_f32_32x32x16_bf16 v[34:49], v[114:117], v[142:145], v[34:49]
	v_add_f32_e32 v50, v82, v83
	v_add_f32_e32 v50, v84, v50
	v_add_f32_e32 v50, v85, v50
	v_add_f32_e32 v50, v86, v50
	v_add_f32_e32 v50, v87, v50
	v_cvt_pk_bf16_f32 v158, v82, v83
	v_cvt_pk_bf16_f32 v159, v84, v85
	ds_read_b64_tr_b16 v[102:103], v208 offset:28672
	ds_read_b64_tr_b16 v[104:105], v208 offset:29184
	v_add_f32_e32 v50, v88, v50
	v_add_f32_e32 v50, v89, v50
	v_add_f32_e32 v50, v90, v50
	v_add_f32_e32 v50, v91, v50
	v_cvt_pk_bf16_f32 v160, v86, v87
	v_cvt_pk_bf16_f32 v161, v88, v89
	ds_read_b64_tr_b16 v[98:99], v208 offset:25600
	ds_read_b64_tr_b16 v[100:101], v208 offset:26112
	v_mfma_f32_32x32x16_bf16 v[34:49], v[110:113], v[138:141], v[34:49]
	v_add_f32_e32 v50, v92, v50
	v_add_f32_e32 v50, v93, v50
	v_add_f32_e32 v50, v94, v50
	v_add_f32_e32 v50, v95, v50
	v_cvt_pk_bf16_f32 v154, v90, v91
	v_cvt_pk_bf16_f32 v155, v92, v93
	ds_read_b64_tr_b16 v[90:91], v208 offset:29696
	ds_read_b64_tr_b16 v[92:93], v208 offset:30208
	v_add_f32_e32 v50, v96, v50
	v_add_f32_e32 v50, v97, v50
	v_add_f32_e32 v50, v66, v50
	v_add_f32_e32 v50, v67, v50
	v_cvt_pk_bf16_f32 v156, v94, v95
	v_cvt_pk_bf16_f32 v157, v96, v97
	ds_read_b64_tr_b16 v[86:87], v208 offset:26624
	ds_read_b64_tr_b16 v[88:89], v208 offset:27136
	v_mfma_f32_32x32x16_bf16 v[34:49], v[106:109], v[134:137], v[34:49]
	v_add_f32_e32 v50, v68, v50
	v_add_f32_e32 v50, v69, v50
	v_add_f32_e32 v50, v70, v50
	v_add_f32_e32 v50, v71, v50
	v_cvt_pk_bf16_f32 v150, v66, v67
	v_cvt_pk_bf16_f32 v151, v68, v69
	ds_read_b64_tr_b16 v[82:83], v208 offset:30720
	ds_read_b64_tr_b16 v[84:85], v208 offset:31232
	v_add_f32_e32 v50, v72, v50
	v_add_f32_e32 v50, v73, v50
	v_add_f32_e32 v50, v74, v50
	v_add_f32_e32 v50, v75, v50
	v_cvt_pk_bf16_f32 v152, v70, v71
	v_cvt_pk_bf16_f32 v153, v72, v73
	ds_read_b64_tr_b16 v[70:71], v208 offset:27648
	ds_read_b64_tr_b16 v[72:73], v208 offset:28160
	v_mfma_f32_32x32x16_bf16 v[34:49], v[58:61], v[130:133], v[34:49]
	v_add_f32_e32 v50, v76, v50
	v_add_f32_e32 v50, v77, v50
	v_add_f32_e32 v50, v78, v50
	v_add_f32_e32 v50, v79, v50
	v_cvt_pk_bf16_f32 v146, v74, v75
	v_cvt_pk_bf16_f32 v147, v76, v77
	ds_read_b64_tr_b16 v[66:67], v208 offset:31744
	ds_read_b64_tr_b16 v[68:69], v208 offset:32256
	s_nop 3
	v_add_f32_e32 v42, v80, v50
	v_add_f32_e32 v42, v81, v42
	v_add_f32_e32 v42, 0, v42
	v_cvt_pk_bf16_f32 v148, v78, v79
	v_cvt_pk_bf16_f32 v149, v80, v81
	v_max_f32_e32 v44, v37, v37
	v_max_f32_e32 v45, v36, v36
	v_add_f32_e32 v74, v118, v42
	v_mov_b32_e32 v42, 0xff800000
	v_max_f32_e32 v44, v45, v44
	v_max3_f32 v43, v34, v35, v42
	v_max3_f32 v44, v44, v42, v40
	v_max3_f32 v43, v43, v38, v39
	v_max3_f32 v44, v44, v41, v42
	v_max3_f32 v43, v43, v42, v44
	v_mov_b32_e32 v44, v43
	s_nop 1
	v_permlane32_swap_b32_e32 v43, v44
	v_max_f32_e32 v44, v44, v44
	v_max_f32_e32 v43, v43, v43
	v_max_f32_e32 v43, v43, v44
	v_cmp_lt_f32_e32 vcc, s82, v43
	s_cmp_lg_u64 vcc, 0
	s_cselect_b64 s[60:61], -1, 0
	s_cbranch_vccnz .LBB0_2619

.LBB0_4093:
	ds_read_b64_tr_b16 v[166:167], v209 offset:40960
	ds_read_b64_tr_b16 v[168:169], v209 offset:41472
	v_mfma_f32_32x32x16_bf16 v[114:129], v[58:61], v[142:145], v[34:49]
	v_add_f32_e32 v50, v98, v99
	v_add_f32_e32 v50, v100, v50
	v_add_f32_e32 v50, v101, v50
	v_add_f32_e32 v50, v102, v50
	v_add_f32_e32 v50, v103, v50
	v_cvt_pk_bf16_f32 v158, v98, v99
	v_cvt_pk_bf16_f32 v159, v100, v101
	ds_read_b64_tr_b16 v[162:163], v209 offset:45056
	ds_read_b64_tr_b16 v[164:165], v209 offset:45568
	v_add_f32_e32 v50, v104, v50
	v_add_f32_e32 v50, v105, v50
	v_add_f32_e32 v50, v106, v50
	v_add_f32_e32 v66, v107, v50
	v_mfma_f32_32x32x16_bf16 v[50:65], v[182:185], v[142:145], v[34:49]
	v_cvt_pk_bf16_f32 v160, v102, v103
	v_cvt_pk_bf16_f32 v161, v104, v105
	ds_read_b64_tr_b16 v[102:103], v209 offset:41984
	ds_read_b64_tr_b16 v[104:105], v209 offset:42496
	v_mfma_f32_32x32x16_bf16 v[114:129], v[186:189], v[138:141], v[114:129]
	v_add_f32_e32 v66, v108, v66
	v_add_f32_e32 v66, v109, v66
	v_add_f32_e32 v66, v110, v66
	v_add_f32_e32 v66, v111, v66
	v_cvt_pk_bf16_f32 v154, v106, v107
	v_cvt_pk_bf16_f32 v155, v108, v109
	ds_read_b64_tr_b16 v[98:99], v209 offset:46080
	ds_read_b64_tr_b16 v[100:101], v209 offset:46592
	v_mfma_f32_32x32x16_bf16 v[50:65], v[78:81], v[138:141], v[50:65]
	v_add_f32_e32 v66, v112, v66
	v_add_f32_e32 v66, v113, v66
	v_add_f32_e32 v66, v82, v66
	v_add_f32_e32 v66, v83, v66
	v_cvt_pk_bf16_f32 v156, v110, v111
	v_cvt_pk_bf16_f32 v157, v112, v113
	ds_read_b64_tr_b16 v[78:79], v209 offset:43008
	ds_read_b64_tr_b16 v[80:81], v209 offset:43520
	v_mfma_f32_32x32x16_bf16 v[114:129], v[74:77], v[134:137], v[114:129]
	v_add_f32_e32 v66, v84, v66
	v_add_f32_e32 v66, v85, v66
	v_add_f32_e32 v66, v86, v66
	v_add_f32_e32 v66, v87, v66
	v_cvt_pk_bf16_f32 v150, v82, v83
	v_cvt_pk_bf16_f32 v151, v84, v85
	ds_read_b64_tr_b16 v[74:75], v209 offset:47104
	ds_read_b64_tr_b16 v[76:77], v209 offset:47616
	v_mfma_f32_32x32x16_bf16 v[50:65], v[174:177], v[134:137], v[50:65]
	v_add_f32_e32 v66, v88, v66
	v_add_f32_e32 v66, v89, v66
	v_add_f32_e32 v66, v90, v66
	v_add_f32_e32 v66, v91, v66
	v_cvt_pk_bf16_f32 v152, v86, v87
	v_cvt_pk_bf16_f32 v153, v88, v89
	ds_read_b64_tr_b16 v[70:71], v209 offset:44032
	ds_read_b64_tr_b16 v[72:73], v209 offset:44544
	v_mfma_f32_32x32x16_bf16 v[114:129], v[178:181], v[130:133], v[114:129]
	v_add_f32_e32 v66, v92, v66
	v_add_f32_e32 v66, v93, v66
	v_add_f32_e32 v66, v94, v66
	v_add_f32_e32 v82, v95, v66
	v_cvt_pk_bf16_f32 v146, v90, v91
	v_cvt_pk_bf16_f32 v147, v92, v93
	ds_read_b64_tr_b16 v[66:67], v209 offset:48128
	ds_read_b64_tr_b16 v[68:69], v209 offset:48640
	v_mfma_f32_32x32x16_bf16 v[50:65], v[170:173], v[130:133], v[50:65]
	v_add_f32_e32 v82, v96, v82
	v_add_f32_e32 v82, v97, v82
	v_add_f32_e32 v82, 0, v82
	v_cvt_pk_bf16_f32 v148, v94, v95
	v_cvt_pk_bf16_f32 v149, v96, v97
	s_cmp_lg_u32 0, -1
	s_cselect_b32 s15, 0, 0
	v_add_f32_e32 v182, v197, v82
	v_lshl_add_u64 v[82:83], v[194:195], 0, s[38:39]
	s_add_i32 s15, s15, s69
	s_add_i32 s15, s15, 0x8000
	s_mov_b32 s18, m0
	s_mov_b32 m0, s15
	s_nop 0
	global_load_lds_dwordx4 v[82:83], off
	s_mov_b32 m0, s18
	v_max_f32_e32 v82, v115, v115
	v_max_f32_e32 v83, v114, v114
	v_max_f32_e32 v82, v83, v82
	v_max3_f32 v83, v116, v117, v51
	v_max3_f32 v82, v82, v50, v52
	v_max3_f32 v82, v82, v53, v118
	v_max3_f32 v83, v83, v120, v121
	v_max3_f32 v82, v82, v119, v54
	v_max3_f32 v83, v83, v56, v57
	v_max3_f32 v82, v82, v55, v122
	v_max3_f32 v83, v83, v124, v125
	v_max3_f32 v82, v82, v123, v58
	v_max3_f32 v83, v83, v60, v61
	v_max3_f32 v82, v82, v59, v126
	v_max3_f32 v83, v83, v128, v129
	v_max3_f32 v82, v82, v127, v62
	v_max3_f32 v83, v83, v64, v65
	v_max3_f32 v82, v82, v63, v83
	v_mov_b32_e32 v83, v82
	s_nop 1
	v_permlane32_swap_b32_e32 v82, v83
	v_max_f32_e32 v83, v83, v83
	v_max_f32_e32 v82, v82, v82
	v_max_f32_e32 v82, v82, v83
	v_cmp_lt_f32_e32 vcc, s82, v82
	s_cmp_lg_u64 vcc, 0
	s_cselect_b64 s[60:61], -1, 0
	s_cbranch_vccnz .LBB0_4200

.LBB0_4134:
	ds_read_b64_tr_b16 v[166:167], v208 offset:32768
	ds_read_b64_tr_b16 v[168:169], v208 offset:33280
	v_mfma_f32_32x32x16_bf16 v[114:129], v[58:61], v[142:145], v[34:49]
	v_add_f32_e32 v50, v98, v99
	v_add_f32_e32 v50, v100, v50
	v_add_f32_e32 v50, v101, v50
	v_add_f32_e32 v50, v102, v50
	v_add_f32_e32 v50, v103, v50
	v_cvt_pk_bf16_f32 v158, v98, v99
	v_cvt_pk_bf16_f32 v159, v100, v101
	ds_read_b64_tr_b16 v[162:163], v208 offset:36864
	ds_read_b64_tr_b16 v[164:165], v208 offset:37376
	v_add_f32_e32 v50, v104, v50
	v_add_f32_e32 v50, v105, v50
	v_add_f32_e32 v50, v106, v50
	v_add_f32_e32 v66, v107, v50
	v_mfma_f32_32x32x16_bf16 v[50:65], v[182:185], v[142:145], v[34:49]
	v_cvt_pk_bf16_f32 v160, v102, v103
	v_cvt_pk_bf16_f32 v161, v104, v105
	ds_read_b64_tr_b16 v[102:103], v208 offset:33792
	ds_read_b64_tr_b16 v[104:105], v208 offset:34304
	v_mfma_f32_32x32x16_bf16 v[114:129], v[186:189], v[138:141], v[114:129]
	v_add_f32_e32 v66, v108, v66
	v_add_f32_e32 v66, v109, v66
	v_add_f32_e32 v66, v110, v66
	v_add_f32_e32 v66, v111, v66
	v_cvt_pk_bf16_f32 v154, v106, v107
	v_cvt_pk_bf16_f32 v155, v108, v109
	ds_read_b64_tr_b16 v[98:99], v208 offset:37888
	ds_read_b64_tr_b16 v[100:101], v208 offset:38400
	v_mfma_f32_32x32x16_bf16 v[50:65], v[78:81], v[138:141], v[50:65]
	v_add_f32_e32 v66, v112, v66
	v_add_f32_e32 v66, v113, v66
	v_add_f32_e32 v66, v82, v66
	v_add_f32_e32 v66, v83, v66
	v_cvt_pk_bf16_f32 v156, v110, v111
	v_cvt_pk_bf16_f32 v157, v112, v113
	ds_read_b64_tr_b16 v[78:79], v208 offset:34816
	ds_read_b64_tr_b16 v[80:81], v208 offset:35328
	v_mfma_f32_32x32x16_bf16 v[114:129], v[74:77], v[134:137], v[114:129]
	v_add_f32_e32 v66, v84, v66
	v_add_f32_e32 v66, v85, v66
	v_add_f32_e32 v66, v86, v66
	v_add_f32_e32 v66, v87, v66
	v_cvt_pk_bf16_f32 v150, v82, v83
	v_cvt_pk_bf16_f32 v151, v84, v85
	ds_read_b64_tr_b16 v[74:75], v208 offset:38912
	ds_read_b64_tr_b16 v[76:77], v208 offset:39424
	v_mfma_f32_32x32x16_bf16 v[50:65], v[174:177], v[134:137], v[50:65]
	v_add_f32_e32 v66, v88, v66
	v_add_f32_e32 v66, v89, v66
	v_add_f32_e32 v66, v90, v66
	v_add_f32_e32 v66, v91, v66
	v_cvt_pk_bf16_f32 v152, v86, v87
	v_cvt_pk_bf16_f32 v153, v88, v89
	ds_read_b64_tr_b16 v[70:71], v208 offset:35840
	ds_read_b64_tr_b16 v[72:73], v208 offset:36352
	v_mfma_f32_32x32x16_bf16 v[114:129], v[178:181], v[130:133], v[114:129]
	v_add_f32_e32 v66, v92, v66
	v_add_f32_e32 v66, v93, v66
	v_add_f32_e32 v66, v94, v66
	v_add_f32_e32 v82, v95, v66
	v_cvt_pk_bf16_f32 v146, v90, v91
	v_cvt_pk_bf16_f32 v147, v92, v93
	ds_read_b64_tr_b16 v[66:67], v208 offset:39936
	ds_read_b64_tr_b16 v[68:69], v208 offset:40448
	v_mfma_f32_32x32x16_bf16 v[50:65], v[170:173], v[130:133], v[50:65]
	v_add_f32_e32 v82, v96, v82
	v_add_f32_e32 v82, v97, v82
	v_add_f32_e32 v82, 0, v82
	v_cvt_pk_bf16_f32 v148, v94, v95
	v_cvt_pk_bf16_f32 v149, v96, v97
	s_nop 0
	v_add_f32_e32 v182, v196, v82
	v_lshl_add_u64 v[82:83], v[194:195], 0, s[44:45]
	s_mov_b32 s15, m0
	s_mov_b32 m0, s69
	s_nop 0
	global_load_lds_dwordx4 v[82:83], off
	s_mov_b32 m0, s15
	v_max_f32_e32 v82, v115, v115
	v_max_f32_e32 v83, v114, v114
	v_max_f32_e32 v82, v83, v82
	s_nop 0
	v_max3_f32 v83, v116, v117, v51
	v_max3_f32 v82, v82, v50, v52
	v_max3_f32 v82, v82, v53, v118
	v_max3_f32 v83, v83, v120, v121
	v_max3_f32 v82, v82, v119, v54
	v_max3_f32 v83, v83, v56, v57
	v_max3_f32 v82, v82, v55, v122
	v_max3_f32 v83, v83, v124, v125
	v_max3_f32 v82, v82, v123, v58
	v_max3_f32 v83, v83, v60, v61
	v_max3_f32 v82, v82, v59, v126
	v_max3_f32 v83, v83, v128, v129
	v_max3_f32 v82, v82, v127, v62
	v_max3_f32 v83, v83, v64, v65
	v_max3_f32 v82, v82, v63, v83
	v_mov_b32_e32 v83, v82
	s_nop 1
	v_permlane32_swap_b32_e32 v82, v83
	v_max_f32_e32 v83, v83, v83
	v_max_f32_e32 v82, v82, v82
	v_max_f32_e32 v82, v82, v83
	v_cmp_lt_f32_e32 vcc, s82, v82
	s_cmp_lg_u64 vcc, 0
	s_cselect_b64 s[60:61], -1, 0
	s_cbranch_vccnz .LBB0_4212

.LBB0_4137:
	ds_read_b64_tr_b16 v[162:163], v208 offset:40960
	ds_read_b64_tr_b16 v[164:165], v208 offset:41472
	v_mfma_f32_32x32x16_bf16 v[82:97], v[110:113], v[142:145], v[34:49]
	v_add_f32_e32 v66, v114, v115
	v_add_f32_e32 v66, v116, v66
	v_add_f32_e32 v66, v117, v66
	v_add_f32_e32 v66, v118, v66
	v_add_f32_e32 v66, v119, v66
	v_cvt_pk_bf16_f32 v158, v114, v115
	v_cvt_pk_bf16_f32 v159, v116, v117
	ds_read_b64_tr_b16 v[114:115], v208 offset:45056
	ds_read_b64_tr_b16 v[116:117], v208 offset:45568
	v_add_f32_e32 v66, v120, v66
	v_add_f32_e32 v66, v121, v66
	v_add_f32_e32 v66, v122, v66
	v_add_f32_e32 v146, v123, v66
	v_mfma_f32_32x32x16_bf16 v[66:81], v[106:109], v[142:145], v[34:49]
	v_cvt_pk_bf16_f32 v160, v118, v119
	v_cvt_pk_bf16_f32 v161, v120, v121
	ds_read_b64_tr_b16 v[110:111], v208 offset:41984
	ds_read_b64_tr_b16 v[112:113], v208 offset:42496
	v_mfma_f32_32x32x16_bf16 v[82:97], v[178:181], v[138:141], v[82:97]
	v_add_f32_e32 v106, v124, v146
	v_add_f32_e32 v106, v125, v106
	v_add_f32_e32 v106, v126, v106
	v_add_f32_e32 v118, v127, v106
	v_cvt_pk_bf16_f32 v154, v122, v123
	v_cvt_pk_bf16_f32 v155, v124, v125
	ds_read_b64_tr_b16 v[106:107], v208 offset:46080
	ds_read_b64_tr_b16 v[108:109], v208 offset:46592
	v_mfma_f32_32x32x16_bf16 v[66:81], v[102:105], v[138:141], v[66:81]
	v_add_f32_e32 v118, v128, v118
	v_add_f32_e32 v118, v129, v118
	v_add_f32_e32 v118, v50, v118
	v_add_f32_e32 v118, v51, v118
	v_cvt_pk_bf16_f32 v156, v126, v127
	v_cvt_pk_bf16_f32 v157, v128, v129
	ds_read_b64_tr_b16 v[102:103], v208 offset:43008
	ds_read_b64_tr_b16 v[104:105], v208 offset:43520
	v_mfma_f32_32x32x16_bf16 v[82:97], v[98:101], v[134:137], v[82:97]
	v_add_f32_e32 v118, v52, v118
	v_add_f32_e32 v118, v53, v118
	v_add_f32_e32 v118, v54, v118
	v_add_f32_e32 v118, v55, v118
	v_cvt_pk_bf16_f32 v150, v50, v51
	v_cvt_pk_bf16_f32 v151, v52, v53
	ds_read_b64_tr_b16 v[98:99], v208 offset:47104
	ds_read_b64_tr_b16 v[100:101], v208 offset:47616
	v_mfma_f32_32x32x16_bf16 v[66:81], v[170:173], v[134:137], v[66:81]
	v_add_f32_e32 v50, v56, v118
	v_add_f32_e32 v50, v57, v50
	v_add_f32_e32 v50, v58, v50
	v_add_f32_e32 v50, v59, v50
	v_cvt_pk_bf16_f32 v152, v54, v55
	v_cvt_pk_bf16_f32 v153, v56, v57
	ds_read_b64_tr_b16 v[54:55], v208 offset:44032
	ds_read_b64_tr_b16 v[56:57], v208 offset:44544
	v_mfma_f32_32x32x16_bf16 v[82:97], v[174:177], v[130:133], v[82:97]
	v_add_f32_e32 v50, v60, v50
	v_add_f32_e32 v50, v61, v50
	v_add_f32_e32 v50, v62, v50
	v_add_f32_e32 v118, v63, v50
	v_cvt_pk_bf16_f32 v146, v58, v59
	v_cvt_pk_bf16_f32 v147, v60, v61
	ds_read_b64_tr_b16 v[50:51], v208 offset:48128
	ds_read_b64_tr_b16 v[52:53], v208 offset:48640
	v_mfma_f32_32x32x16_bf16 v[66:81], v[166:169], v[130:133], v[66:81]
	v_add_f32_e32 v58, v64, v118
	v_add_f32_e32 v58, v65, v58
	v_add_f32_e32 v58, 0, v58
	v_cvt_pk_bf16_f32 v148, v62, v63
	v_cvt_pk_bf16_f32 v149, v64, v65
	s_cmp_lg_u32 0, -1
	s_cselect_b32 s15, 0, 0
	v_add_f32_e32 v118, v182, v58
	v_lshl_add_u64 v[58:59], v[194:195], 0, s[40:41]
	s_add_i32 s15, s15, s68
	s_add_i32 s15, s15, 0x8000
	s_mov_b32 s18, m0
	s_mov_b32 m0, s15
	s_nop 0
	global_load_lds_dwordx4 v[58:59], off
	s_mov_b32 m0, s18
	v_max_f32_e32 v58, v83, v83
	v_max_f32_e32 v59, v82, v82
	v_max_f32_e32 v58, v59, v58
	v_max3_f32 v59, v84, v85, v67
	v_max3_f32 v58, v58, v66, v68
	v_max3_f32 v58, v58, v69, v86
	v_max3_f32 v59, v59, v88, v89
	v_max3_f32 v58, v58, v87, v70
	v_max3_f32 v59, v59, v72, v73
	v_max3_f32 v58, v58, v71, v90
	v_max3_f32 v59, v59, v92, v93
	v_max3_f32 v58, v58, v91, v74
	v_max3_f32 v59, v59, v76, v77
	v_max3_f32 v58, v58, v75, v94
	v_max3_f32 v59, v59, v96, v97
	v_max3_f32 v58, v58, v95, v78
	v_max3_f32 v59, v59, v80, v81
	v_max3_f32 v58, v58, v79, v59
	v_mov_b32_e32 v59, v58
	s_nop 1
	v_permlane32_swap_b32_e32 v58, v59
	v_max_f32_e32 v59, v59, v59
	v_max_f32_e32 v58, v58, v58
	v_max_f32_e32 v58, v58, v59
	v_cmp_lt_f32_e32 vcc, s82, v58
	s_cmp_lg_u64 vcc, 0
	s_cselect_b64 s[60:61], -1, 0
	s_cbranch_vccnz .LBB0_4215
